# MLA attention: counted vmcnt + 2-tile software pipelining; leaner SwiGLU epilogue (rsq form, pairwise ssq sum, prefetched ssq loads)
# speedup vs baseline: 1.0008x; 1.0008x over previous
; __device__ __forceinline__ unsigned cvtpk(float lo, float hi) { f32x2_t v = {lo, hi}; bf16x2_t b = __builtin_convertvector(v, bf16x2_t); return __builtin_bit_cast(unsigned, b); }
;     __device__ __forceinline__ void operator()(const f32x4 (&acc)[2][2][4][2], const Unit& u, int wr, int wc, int fr, int fq) const {
;         const int row0 = u.pm * BM + wr * 64 + fr, col0 = u.pn * 128 + wc * 32 + 8 * fq;
; #pragma unroll
;         for (int ai = 0; ai < 2; ++ai)
; #pragma unroll
;             for (int m = 0; m < 4; ++m) {
;                 const int row = row0 + ai * HALF + m * 16;
;                 const float rs = 1.0f / sqrtf(ssq_sum(ssq + (size_t)row * 16) * (1.0f / DM) + EPS);
;                 float hv[8];
; #pragma unroll
;                 for (int n = 0; n < 2; ++n)
; #pragma unroll
;                     for (int e = 0; e < 4; ++e) {
;                         const float gg = acc[ai][0][m][n][e] * rs, uu = acc[ai][1][m][n][e] * rs;
;                         const float den = 1.0f + __builtin_amdgcn_exp2f(-gg * LOG2E);
;                         hv[n * 4 + e] = gg * uu * __builtin_amdgcn_rcpf(den);
;                     }
;                 u32x4 w; w.x = cvtpk(hv[0], hv[1]); w.y = cvtpk(hv[2], hv[3]); w.z = cvtpk(hv[4], hv[5]); w.w = cvtpk(hv[6], hv[7]);
;                 *(u32x4*)(H + (size_t)row * DFF + col0) = w;
;             }
.LBB0_244:
	v_lshl_add_u32 v148, s8, 8, v152
	v_ashrrev_i32_e32 v149, 31, v148
	v_lshlrev_b64 v[144:145], 6, v[148:149]
	v_lshl_add_u64 v[144:145], s[14:15], 0, v[144:145]
	global_load_dwordx4 v[160:163], v[144:145], off
	global_load_dwordx4 v[164:167], v[144:145], off offset:16
	global_load_dwordx4 v[168:171], v[144:145], off offset:32
	global_load_dwordx4 v[172:175], v[144:145], off offset:48
	v_mov_b64_e32 v[146:147], s[16:17]
	v_mad_i64_i32 v[176:177], s[8:9], v148, s56, v[146:147]
	v_lshl_or_b32 v150, s2, 7, v154
	v_mov_b32_e32 v151, 0
	v_lshlrev_b64 v[150:151], 1, v[150:151]
	v_lshl_add_u64 v[176:177], v[176:177], 0, v[150:151]
	s_mov_b32 s8, 0x2000
	s_mov_b32 s9, 0
	v_lshl_add_u64 v[146:147], v[144:145], 0, s[8:9]
	s_waitcnt vmcnt(0)
	v_pk_add_f32 v[160:161], v[160:161], v[162:163]
	v_pk_add_f32 v[164:165], v[164:165], v[166:167]
	v_pk_add_f32 v[168:169], v[168:169], v[170:171]
	v_pk_add_f32 v[172:173], v[172:173], v[174:175]
	v_pk_add_f32 v[160:161], v[160:161], v[164:165]
	v_pk_add_f32 v[168:169], v[168:169], v[172:173]
	v_pk_add_f32 v[160:161], v[160:161], v[168:169]
	v_add_f32_e32 v149, v160, v161
	v_fmamk_f32 v149, v149, 0x3a800000, v158
	v_rsq_f32_e32 v150, v149
	global_load_dwordx4 v[160:163], v[144:145], off offset:1024
	global_load_dwordx4 v[164:167], v[144:145], off offset:1040
	global_load_dwordx4 v[168:171], v[144:145], off offset:1056
	global_load_dwordx4 v[172:175], v[144:145], off offset:1072
	v_pk_mul_f32 v[116:117], v[124:125], v[116:117]
	v_pk_mul_f32 v[118:119], v[126:127], v[118:119]
	v_pk_mul_f32 v[112:113], v[120:121], v[112:113]
	v_pk_mul_f32 v[114:115], v[122:123], v[114:115]
	v_mul_f32_e32 v150, 0xbfb8aa3b, v150
	v_mov_b32_e32 v151, v149
	v_pk_mul_f32 v[124:125], v[124:125], v[150:151] op_sel_hi:[1,0]
	v_pk_mul_f32 v[126:127], v[126:127], v[150:151] op_sel_hi:[1,0]
	v_pk_mul_f32 v[120:121], v[120:121], v[150:151] op_sel_hi:[1,0]
	v_pk_mul_f32 v[122:123], v[122:123], v[150:151] op_sel_hi:[1,0]
	v_exp_f32_e32 v124, v124
	v_exp_f32_e32 v125, v125
	v_exp_f32_e32 v126, v126
	v_exp_f32_e32 v127, v127
	v_exp_f32_e32 v120, v120
	v_exp_f32_e32 v121, v121
	v_exp_f32_e32 v122, v122
	v_exp_f32_e32 v123, v123
	v_fma_f32 v124, v124, v149, v149
	v_fma_f32 v125, v125, v149, v149
	v_fma_f32 v126, v126, v149, v149
	v_fma_f32 v127, v127, v149, v149
	v_fma_f32 v120, v120, v149, v149
	v_fma_f32 v121, v121, v149, v149
	v_fma_f32 v122, v122, v149, v149
	v_fma_f32 v123, v123, v149, v149
	v_rcp_f32_e32 v124, v124
	v_rcp_f32_e32 v125, v125
	v_rcp_f32_e32 v126, v126
	v_rcp_f32_e32 v127, v127
	v_rcp_f32_e32 v120, v120
	v_rcp_f32_e32 v121, v121
	v_rcp_f32_e32 v122, v122
	v_rcp_f32_e32 v123, v123
	v_pk_mul_f32 v[116:117], v[116:117], v[124:125]
	v_pk_mul_f32 v[118:119], v[118:119], v[126:127]
	v_pk_mul_f32 v[112:113], v[112:113], v[120:121]
	v_pk_mul_f32 v[114:115], v[114:115], v[122:123]
	v_cvt_pk_bf16_f32 v124, v116, v117
	v_cvt_pk_bf16_f32 v125, v118, v119
	v_cvt_pk_bf16_f32 v126, v112, v113
	v_cvt_pk_bf16_f32 v127, v114, v115
	global_store_dwordx4 v[176:177], v[124:127], off
	s_waitcnt vmcnt(1)
	v_pk_add_f32 v[160:161], v[160:161], v[162:163]
	v_pk_add_f32 v[164:165], v[164:165], v[166:167]
	v_pk_add_f32 v[168:169], v[168:169], v[170:171]
	v_pk_add_f32 v[172:173], v[172:173], v[174:175]
	v_pk_add_f32 v[160:161], v[160:161], v[164:165]
	v_pk_add_f32 v[168:169], v[168:169], v[172:173]
	v_pk_add_f32 v[160:161], v[160:161], v[168:169]
	v_add_f32_e32 v149, v160, v161
	v_fmamk_f32 v149, v149, 0x3a800000, v158
	v_rsq_f32_e32 v150, v149
	global_load_dwordx4 v[160:163], v[144:145], off offset:2048
	global_load_dwordx4 v[164:167], v[144:145], off offset:2064
	global_load_dwordx4 v[168:171], v[144:145], off offset:2080
	global_load_dwordx4 v[172:175], v[144:145], off offset:2096
	v_pk_mul_f32 v[100:101], v[108:109], v[100:101]
	v_pk_mul_f32 v[102:103], v[110:111], v[102:103]
	v_pk_mul_f32 v[96:97], v[104:105], v[96:97]
	v_pk_mul_f32 v[98:99], v[106:107], v[98:99]
	v_mul_f32_e32 v150, 0xbfb8aa3b, v150
	v_mov_b32_e32 v151, v149
	v_pk_mul_f32 v[108:109], v[108:109], v[150:151] op_sel_hi:[1,0]
	v_pk_mul_f32 v[110:111], v[110:111], v[150:151] op_sel_hi:[1,0]
	v_pk_mul_f32 v[104:105], v[104:105], v[150:151] op_sel_hi:[1,0]
	v_pk_mul_f32 v[106:107], v[106:107], v[150:151] op_sel_hi:[1,0]
	v_exp_f32_e32 v108, v108
	v_exp_f32_e32 v109, v109
	v_exp_f32_e32 v110, v110
	v_exp_f32_e32 v111, v111
	v_exp_f32_e32 v104, v104
	v_exp_f32_e32 v105, v105
	v_exp_f32_e32 v106, v106
	v_exp_f32_e32 v107, v107
	v_fma_f32 v108, v108, v149, v149
	v_fma_f32 v109, v109, v149, v149
	v_fma_f32 v110, v110, v149, v149
	v_fma_f32 v111, v111, v149, v149
	v_fma_f32 v104, v104, v149, v149
	v_fma_f32 v105, v105, v149, v149
	v_fma_f32 v106, v106, v149, v149
	v_fma_f32 v107, v107, v149, v149
	v_rcp_f32_e32 v108, v108
	v_rcp_f32_e32 v109, v109
	v_rcp_f32_e32 v110, v110
	v_rcp_f32_e32 v111, v111
	v_rcp_f32_e32 v104, v104
	v_rcp_f32_e32 v105, v105
	v_rcp_f32_e32 v106, v106
	v_rcp_f32_e32 v107, v107
	s_mov_b32 s8, 0x16000
	v_pk_mul_f32 v[100:101], v[100:101], v[108:109]
	v_pk_mul_f32 v[102:103], v[102:103], v[110:111]
	v_pk_mul_f32 v[96:97], v[96:97], v[104:105]
	v_pk_mul_f32 v[98:99], v[98:99], v[106:107]
	v_cvt_pk_bf16_f32 v108, v100, v101
	v_cvt_pk_bf16_f32 v109, v102, v103
	v_cvt_pk_bf16_f32 v110, v96, v97
	v_cvt_pk_bf16_f32 v111, v98, v99
	v_lshl_add_u64 v[178:179], v[176:177], 0, s[8:9]
	global_store_dwordx4 v[178:179], v[108:111], off
	s_waitcnt vmcnt(1)
; __device__ __forceinline__ unsigned cvtpk(float lo, float hi) { f32x2_t v = {lo, hi}; bf16x2_t b = __builtin_convertvector(v, bf16x2_t); return __builtin_bit_cast(unsigned, b); }
;     __device__ __forceinline__ void operator()(const f32x4 (&acc)[2][2][4][2], const Unit& u, int wr, int wc, int fr, int fq) const {
;         const int row0 = u.pm * BM + wr * 64 + fr, col0 = u.pn * 128 + wc * 32 + 8 * fq;
; #pragma unroll
;         for (int ai = 0; ai < 2; ++ai)
; #pragma unroll
;             for (int m = 0; m < 4; ++m) {
;                 const int row = row0 + ai * HALF + m * 16;
;                 const float rs = 1.0f / sqrtf(ssq_sum(ssq + (size_t)row * 16) * (1.0f / DM) + EPS);
;                 float hv[8];
; #pragma unroll
;                 for (int n = 0; n < 2; ++n)
; #pragma unroll
;                     for (int e = 0; e < 4; ++e) {
;                         const float gg = acc[ai][0][m][n][e] * rs, uu = acc[ai][1][m][n][e] * rs;
;                         const float den = 1.0f + __builtin_amdgcn_exp2f(-gg * LOG2E);
;                         hv[n * 4 + e] = gg * uu * __builtin_amdgcn_rcpf(den);
;                     }
;                 u32x4 w; w.x = cvtpk(hv[0], hv[1]); w.y = cvtpk(hv[2], hv[3]); w.z = cvtpk(hv[4], hv[5]); w.w = cvtpk(hv[6], hv[7]);
;                 *(u32x4*)(H + (size_t)row * DFF + col0) = w;
;             }
	v_pk_add_f32 v[160:161], v[160:161], v[162:163]
	v_pk_add_f32 v[164:165], v[164:165], v[166:167]
	v_pk_add_f32 v[168:169], v[168:169], v[170:171]
	v_pk_add_f32 v[172:173], v[172:173], v[174:175]
	v_pk_add_f32 v[160:161], v[160:161], v[164:165]
	v_pk_add_f32 v[168:169], v[168:169], v[172:173]
	v_pk_add_f32 v[160:161], v[160:161], v[168:169]
	v_add_f32_e32 v149, v160, v161
	v_fmamk_f32 v149, v149, 0x3a800000, v158
	v_rsq_f32_e32 v150, v149
	global_load_dwordx4 v[160:163], v[144:145], off offset:3072
	global_load_dwordx4 v[164:167], v[144:145], off offset:3088
	global_load_dwordx4 v[168:171], v[144:145], off offset:3104
	global_load_dwordx4 v[172:175], v[144:145], off offset:3120
	v_pk_mul_f32 v[84:85], v[92:93], v[84:85]
	v_pk_mul_f32 v[86:87], v[94:95], v[86:87]
	v_pk_mul_f32 v[80:81], v[88:89], v[80:81]
	v_pk_mul_f32 v[82:83], v[90:91], v[82:83]
	v_mul_f32_e32 v150, 0xbfb8aa3b, v150
	v_mov_b32_e32 v151, v149
	v_pk_mul_f32 v[92:93], v[92:93], v[150:151] op_sel_hi:[1,0]
	v_pk_mul_f32 v[94:95], v[94:95], v[150:151] op_sel_hi:[1,0]
	v_pk_mul_f32 v[88:89], v[88:89], v[150:151] op_sel_hi:[1,0]
	v_pk_mul_f32 v[90:91], v[90:91], v[150:151] op_sel_hi:[1,0]
	v_exp_f32_e32 v92, v92
	v_exp_f32_e32 v93, v93
	v_exp_f32_e32 v94, v94
	v_exp_f32_e32 v95, v95
	v_exp_f32_e32 v88, v88
	v_exp_f32_e32 v89, v89
	v_exp_f32_e32 v90, v90
	v_exp_f32_e32 v91, v91
	v_fma_f32 v92, v92, v149, v149
	v_fma_f32 v93, v93, v149, v149
	v_fma_f32 v94, v94, v149, v149
	v_fma_f32 v95, v95, v149, v149
	v_fma_f32 v88, v88, v149, v149
	v_fma_f32 v89, v89, v149, v149
	v_fma_f32 v90, v90, v149, v149
	v_fma_f32 v91, v91, v149, v149
	v_rcp_f32_e32 v92, v92
	v_rcp_f32_e32 v93, v93
	v_rcp_f32_e32 v94, v94
	v_rcp_f32_e32 v95, v95
	v_rcp_f32_e32 v88, v88
	v_rcp_f32_e32 v89, v89
	v_rcp_f32_e32 v90, v90
	v_rcp_f32_e32 v91, v91
	s_mov_b32 s8, 0x2c000
	v_pk_mul_f32 v[84:85], v[84:85], v[92:93]
	v_pk_mul_f32 v[86:87], v[86:87], v[94:95]
	v_pk_mul_f32 v[80:81], v[80:81], v[88:89]
	v_pk_mul_f32 v[82:83], v[82:83], v[90:91]
	v_cvt_pk_bf16_f32 v92, v84, v85
	v_cvt_pk_bf16_f32 v93, v86, v87
	v_cvt_pk_bf16_f32 v94, v80, v81
	v_cvt_pk_bf16_f32 v95, v82, v83
	v_lshl_add_u64 v[178:179], v[176:177], 0, s[8:9]
	global_store_dwordx4 v[178:179], v[92:95], off
	s_waitcnt vmcnt(1)
	v_pk_add_f32 v[160:161], v[160:161], v[162:163]
	v_pk_add_f32 v[164:165], v[164:165], v[166:167]
	v_pk_add_f32 v[168:169], v[168:169], v[170:171]
	v_pk_add_f32 v[172:173], v[172:173], v[174:175]
	v_pk_add_f32 v[160:161], v[160:161], v[164:165]
	v_pk_add_f32 v[168:169], v[168:169], v[172:173]
	v_pk_add_f32 v[160:161], v[160:161], v[168:169]
	v_add_f32_e32 v149, v160, v161
	v_fmamk_f32 v149, v149, 0x3a800000, v158
	v_rsq_f32_e32 v150, v149
	global_load_dwordx4 v[160:163], v[146:147], off
	global_load_dwordx4 v[164:167], v[146:147], off offset:16
	global_load_dwordx4 v[168:171], v[146:147], off offset:32
	global_load_dwordx4 v[172:175], v[146:147], off offset:48
	v_pk_mul_f32 v[68:69], v[76:77], v[68:69]
	v_pk_mul_f32 v[70:71], v[78:79], v[70:71]
	v_pk_mul_f32 v[64:65], v[72:73], v[64:65]
	v_pk_mul_f32 v[66:67], v[74:75], v[66:67]
	v_mul_f32_e32 v150, 0xbfb8aa3b, v150
	v_mov_b32_e32 v151, v149
	v_pk_mul_f32 v[76:77], v[76:77], v[150:151] op_sel_hi:[1,0]
	v_pk_mul_f32 v[78:79], v[78:79], v[150:151] op_sel_hi:[1,0]
	v_pk_mul_f32 v[72:73], v[72:73], v[150:151] op_sel_hi:[1,0]
	v_pk_mul_f32 v[74:75], v[74:75], v[150:151] op_sel_hi:[1,0]
	v_exp_f32_e32 v76, v76
	v_exp_f32_e32 v77, v77
	v_exp_f32_e32 v78, v78
	v_exp_f32_e32 v79, v79
	v_exp_f32_e32 v72, v72
	v_exp_f32_e32 v73, v73
	v_exp_f32_e32 v74, v74
	v_exp_f32_e32 v75, v75
	v_fma_f32 v76, v76, v149, v149
	v_fma_f32 v77, v77, v149, v149
	v_fma_f32 v78, v78, v149, v149
	v_fma_f32 v79, v79, v149, v149
	v_fma_f32 v72, v72, v149, v149
	v_fma_f32 v73, v73, v149, v149
	v_fma_f32 v74, v74, v149, v149
	v_fma_f32 v75, v75, v149, v149
	v_rcp_f32_e32 v76, v76
	v_rcp_f32_e32 v77, v77
	v_rcp_f32_e32 v78, v78
	v_rcp_f32_e32 v79, v79
	v_rcp_f32_e32 v72, v72
	v_rcp_f32_e32 v73, v73
	v_rcp_f32_e32 v74, v74
	v_rcp_f32_e32 v75, v75
	s_mov_b32 s8, 0x42000
	v_pk_mul_f32 v[68:69], v[68:69], v[76:77]
	v_pk_mul_f32 v[70:71], v[70:71], v[78:79]
	v_pk_mul_f32 v[64:65], v[64:65], v[72:73]
	v_pk_mul_f32 v[66:67], v[66:67], v[74:75]
	v_cvt_pk_bf16_f32 v76, v68, v69
	v_cvt_pk_bf16_f32 v77, v70, v71
	v_cvt_pk_bf16_f32 v78, v64, v65
	v_cvt_pk_bf16_f32 v79, v66, v67
	v_lshl_add_u64 v[178:179], v[176:177], 0, s[8:9]
	global_store_dwordx4 v[178:179], v[76:79], off
	s_waitcnt vmcnt(1)
	v_pk_add_f32 v[160:161], v[160:161], v[162:163]
	v_pk_add_f32 v[164:165], v[164:165], v[166:167]
	v_pk_add_f32 v[168:169], v[168:169], v[170:171]
	v_pk_add_f32 v[172:173], v[172:173], v[174:175]
	v_pk_add_f32 v[160:161], v[160:161], v[164:165]
	v_pk_add_f32 v[168:169], v[168:169], v[172:173]
	v_pk_add_f32 v[160:161], v[160:161], v[168:169]
	v_add_f32_e32 v149, v160, v161
	v_fmamk_f32 v149, v149, 0x3a800000, v158
	v_rsq_f32_e32 v150, v149
	global_load_dwordx4 v[160:163], v[146:147], off offset:1024
	global_load_dwordx4 v[164:167], v[146:147], off offset:1040
	global_load_dwordx4 v[168:171], v[146:147], off offset:1056
	global_load_dwordx4 v[172:175], v[146:147], off offset:1072
	v_pk_mul_f32 v[52:53], v[60:61], v[52:53]
	v_pk_mul_f32 v[54:55], v[62:63], v[54:55]
	v_pk_mul_f32 v[48:49], v[56:57], v[48:49]
	v_pk_mul_f32 v[50:51], v[58:59], v[50:51]
	v_mul_f32_e32 v150, 0xbfb8aa3b, v150
	v_mov_b32_e32 v151, v149
	v_pk_mul_f32 v[60:61], v[60:61], v[150:151] op_sel_hi:[1,0]
	v_pk_mul_f32 v[62:63], v[62:63], v[150:151] op_sel_hi:[1,0]
	v_pk_mul_f32 v[56:57], v[56:57], v[150:151] op_sel_hi:[1,0]
	v_pk_mul_f32 v[58:59], v[58:59], v[150:151] op_sel_hi:[1,0]
	v_exp_f32_e32 v60, v60
	v_exp_f32_e32 v61, v61
	v_exp_f32_e32 v62, v62
	v_exp_f32_e32 v63, v63
	v_exp_f32_e32 v56, v56
	v_exp_f32_e32 v57, v57
	v_exp_f32_e32 v58, v58
	v_exp_f32_e32 v59, v59
	v_fma_f32 v60, v60, v149, v149
	v_fma_f32 v61, v61, v149, v149
	v_fma_f32 v62, v62, v149, v149
	v_fma_f32 v63, v63, v149, v149
	v_fma_f32 v56, v56, v149, v149
	v_fma_f32 v57, v57, v149, v149
	v_fma_f32 v58, v58, v149, v149
	v_fma_f32 v59, v59, v149, v149
	v_rcp_f32_e32 v60, v60
	v_rcp_f32_e32 v61, v61
	v_rcp_f32_e32 v62, v62
	v_rcp_f32_e32 v63, v63
	v_rcp_f32_e32 v56, v56
	v_rcp_f32_e32 v57, v57
	v_rcp_f32_e32 v58, v58
	v_rcp_f32_e32 v59, v59
	s_mov_b32 s8, 0xb0000
	v_pk_mul_f32 v[52:53], v[52:53], v[60:61]
	v_pk_mul_f32 v[54:55], v[54:55], v[62:63]
	v_pk_mul_f32 v[48:49], v[48:49], v[56:57]
	v_pk_mul_f32 v[50:51], v[50:51], v[58:59]
	v_cvt_pk_bf16_f32 v60, v52, v53
	v_cvt_pk_bf16_f32 v61, v54, v55
	v_cvt_pk_bf16_f32 v62, v48, v49
	v_cvt_pk_bf16_f32 v63, v50, v51
	v_lshl_add_u64 v[178:179], v[176:177], 0, s[8:9]
	global_store_dwordx4 v[178:179], v[60:63], off
	s_waitcnt vmcnt(1)
; __device__ __forceinline__ unsigned cvtpk(float lo, float hi) { f32x2_t v = {lo, hi}; bf16x2_t b = __builtin_convertvector(v, bf16x2_t); return __builtin_bit_cast(unsigned, b); }
;     __device__ __forceinline__ void operator()(const f32x4 (&acc)[2][2][4][2], const Unit& u, int wr, int wc, int fr, int fq) const {
;         const int row0 = u.pm * BM + wr * 64 + fr, col0 = u.pn * 128 + wc * 32 + 8 * fq;
; #pragma unroll
;         for (int ai = 0; ai < 2; ++ai)
; #pragma unroll
;             for (int m = 0; m < 4; ++m) {
;                 const int row = row0 + ai * HALF + m * 16;
;                 const float rs = 1.0f / sqrtf(ssq_sum(ssq + (size_t)row * 16) * (1.0f / DM) + EPS);
;                 float hv[8];
; #pragma unroll
;                 for (int n = 0; n < 2; ++n)
; #pragma unroll
;                     for (int e = 0; e < 4; ++e) {
;                         const float gg = acc[ai][0][m][n][e] * rs, uu = acc[ai][1][m][n][e] * rs;
;                         const float den = 1.0f + __builtin_amdgcn_exp2f(-gg * LOG2E);
;                         hv[n * 4 + e] = gg * uu * __builtin_amdgcn_rcpf(den);
;                     }
;                 u32x4 w; w.x = cvtpk(hv[0], hv[1]); w.y = cvtpk(hv[2], hv[3]); w.z = cvtpk(hv[4], hv[5]); w.w = cvtpk(hv[6], hv[7]);
;                 *(u32x4*)(H + (size_t)row * DFF + col0) = w;
;             }
	v_pk_add_f32 v[160:161], v[160:161], v[162:163]
	v_pk_add_f32 v[164:165], v[164:165], v[166:167]
	v_pk_add_f32 v[168:169], v[168:169], v[170:171]
	v_pk_add_f32 v[172:173], v[172:173], v[174:175]
	v_pk_add_f32 v[160:161], v[160:161], v[164:165]
	v_pk_add_f32 v[168:169], v[168:169], v[172:173]
	v_pk_add_f32 v[160:161], v[160:161], v[168:169]
	v_add_f32_e32 v149, v160, v161
	v_fmamk_f32 v149, v149, 0x3a800000, v158
	v_rsq_f32_e32 v150, v149
	global_load_dwordx4 v[160:163], v[146:147], off offset:2048
	global_load_dwordx4 v[164:167], v[146:147], off offset:2064
	global_load_dwordx4 v[168:171], v[146:147], off offset:2080
	global_load_dwordx4 v[172:175], v[146:147], off offset:2096
	v_pk_mul_f32 v[36:37], v[44:45], v[36:37]
	v_pk_mul_f32 v[38:39], v[46:47], v[38:39]
	v_pk_mul_f32 v[32:33], v[40:41], v[32:33]
	v_pk_mul_f32 v[34:35], v[42:43], v[34:35]
	v_mul_f32_e32 v150, 0xbfb8aa3b, v150
	v_mov_b32_e32 v151, v149
	v_pk_mul_f32 v[44:45], v[44:45], v[150:151] op_sel_hi:[1,0]
	v_pk_mul_f32 v[46:47], v[46:47], v[150:151] op_sel_hi:[1,0]
	v_pk_mul_f32 v[40:41], v[40:41], v[150:151] op_sel_hi:[1,0]
	v_pk_mul_f32 v[42:43], v[42:43], v[150:151] op_sel_hi:[1,0]
	v_exp_f32_e32 v44, v44
	v_exp_f32_e32 v45, v45
	v_exp_f32_e32 v46, v46
	v_exp_f32_e32 v47, v47
	v_exp_f32_e32 v40, v40
	v_exp_f32_e32 v41, v41
	v_exp_f32_e32 v42, v42
	v_exp_f32_e32 v43, v43
	v_fma_f32 v44, v44, v149, v149
	v_fma_f32 v45, v45, v149, v149
	v_fma_f32 v46, v46, v149, v149
	v_fma_f32 v47, v47, v149, v149
	v_fma_f32 v40, v40, v149, v149
	v_fma_f32 v41, v41, v149, v149
	v_fma_f32 v42, v42, v149, v149
	v_fma_f32 v43, v43, v149, v149
	v_rcp_f32_e32 v44, v44
	v_rcp_f32_e32 v45, v45
	v_rcp_f32_e32 v46, v46
	v_rcp_f32_e32 v47, v47
	v_rcp_f32_e32 v40, v40
	v_rcp_f32_e32 v41, v41
	v_rcp_f32_e32 v42, v42
	v_rcp_f32_e32 v43, v43
	s_mov_b32 s8, 0xc6000
	v_pk_mul_f32 v[36:37], v[36:37], v[44:45]
	v_pk_mul_f32 v[38:39], v[38:39], v[46:47]
	v_pk_mul_f32 v[32:33], v[32:33], v[40:41]
	v_pk_mul_f32 v[34:35], v[34:35], v[42:43]
	v_cvt_pk_bf16_f32 v44, v36, v37
	v_cvt_pk_bf16_f32 v45, v38, v39
	v_cvt_pk_bf16_f32 v46, v32, v33
	v_cvt_pk_bf16_f32 v47, v34, v35
	v_lshl_add_u64 v[178:179], v[176:177], 0, s[8:9]
	global_store_dwordx4 v[178:179], v[44:47], off
	s_waitcnt vmcnt(1)
	v_pk_add_f32 v[160:161], v[160:161], v[162:163]
	v_pk_add_f32 v[164:165], v[164:165], v[166:167]
	v_pk_add_f32 v[168:169], v[168:169], v[170:171]
	v_pk_add_f32 v[172:173], v[172:173], v[174:175]
	v_pk_add_f32 v[160:161], v[160:161], v[164:165]
	v_pk_add_f32 v[168:169], v[168:169], v[172:173]
	v_pk_add_f32 v[160:161], v[160:161], v[168:169]
	v_add_f32_e32 v149, v160, v161
	v_fmamk_f32 v149, v149, 0x3a800000, v158
	v_rsq_f32_e32 v150, v149
	global_load_dwordx4 v[160:163], v[146:147], off offset:3072
	global_load_dwordx4 v[164:167], v[146:147], off offset:3088
	global_load_dwordx4 v[168:171], v[146:147], off offset:3104
	global_load_dwordx4 v[172:175], v[146:147], off offset:3120
	v_pk_mul_f32 v[20:21], v[28:29], v[20:21]
	v_pk_mul_f32 v[22:23], v[30:31], v[22:23]
	v_pk_mul_f32 v[16:17], v[24:25], v[16:17]
	v_pk_mul_f32 v[18:19], v[26:27], v[18:19]
	v_mul_f32_e32 v150, 0xbfb8aa3b, v150
	v_mov_b32_e32 v151, v149
	v_pk_mul_f32 v[28:29], v[28:29], v[150:151] op_sel_hi:[1,0]
	v_pk_mul_f32 v[30:31], v[30:31], v[150:151] op_sel_hi:[1,0]
	v_pk_mul_f32 v[24:25], v[24:25], v[150:151] op_sel_hi:[1,0]
	v_pk_mul_f32 v[26:27], v[26:27], v[150:151] op_sel_hi:[1,0]
	v_exp_f32_e32 v28, v28
	v_exp_f32_e32 v29, v29
	v_exp_f32_e32 v30, v30
	v_exp_f32_e32 v31, v31
	v_exp_f32_e32 v24, v24
	v_exp_f32_e32 v25, v25
	v_exp_f32_e32 v26, v26
	v_exp_f32_e32 v27, v27
	v_fma_f32 v28, v28, v149, v149
	v_fma_f32 v29, v29, v149, v149
	v_fma_f32 v30, v30, v149, v149
	v_fma_f32 v31, v31, v149, v149
	v_fma_f32 v24, v24, v149, v149
	v_fma_f32 v25, v25, v149, v149
	v_fma_f32 v26, v26, v149, v149
	v_fma_f32 v27, v27, v149, v149
	v_rcp_f32_e32 v28, v28
	v_rcp_f32_e32 v29, v29
	v_rcp_f32_e32 v30, v30
	v_rcp_f32_e32 v31, v31
	v_rcp_f32_e32 v24, v24
	v_rcp_f32_e32 v25, v25
	v_rcp_f32_e32 v26, v26
	v_rcp_f32_e32 v27, v27
	s_mov_b32 s8, 0xdc000
	v_pk_mul_f32 v[20:21], v[20:21], v[28:29]
	v_pk_mul_f32 v[22:23], v[22:23], v[30:31]
	v_pk_mul_f32 v[16:17], v[16:17], v[24:25]
	v_pk_mul_f32 v[18:19], v[18:19], v[26:27]
	v_cvt_pk_bf16_f32 v28, v20, v21
	v_cvt_pk_bf16_f32 v29, v22, v23
	v_cvt_pk_bf16_f32 v30, v16, v17
	v_cvt_pk_bf16_f32 v31, v18, v19
	v_lshl_add_u64 v[178:179], v[176:177], 0, s[8:9]
	global_store_dwordx4 v[178:179], v[28:31], off
	s_waitcnt vmcnt(1)
	v_pk_add_f32 v[160:161], v[160:161], v[162:163]
	v_pk_add_f32 v[164:165], v[164:165], v[166:167]
	v_pk_add_f32 v[168:169], v[168:169], v[170:171]
	v_pk_add_f32 v[172:173], v[172:173], v[174:175]
	v_pk_add_f32 v[160:161], v[160:161], v[164:165]
	v_pk_add_f32 v[168:169], v[168:169], v[172:173]
	v_pk_add_f32 v[160:161], v[160:161], v[168:169]
	v_add_f32_e32 v149, v160, v161
	v_fmamk_f32 v149, v149, 0x3a800000, v158
	v_rsq_f32_e32 v150, v149
	v_pk_mul_f32 v[4:5], v[12:13], v[4:5]
	v_pk_mul_f32 v[6:7], v[14:15], v[6:7]
	v_pk_mul_f32 v[0:1], v[8:9], v[0:1]
	v_pk_mul_f32 v[2:3], v[10:11], v[2:3]
	v_mul_f32_e32 v150, 0xbfb8aa3b, v150
	v_mov_b32_e32 v151, v149
	v_pk_mul_f32 v[12:13], v[12:13], v[150:151] op_sel_hi:[1,0]
	v_pk_mul_f32 v[14:15], v[14:15], v[150:151] op_sel_hi:[1,0]
	v_pk_mul_f32 v[8:9], v[8:9], v[150:151] op_sel_hi:[1,0]
	v_pk_mul_f32 v[10:11], v[10:11], v[150:151] op_sel_hi:[1,0]
	v_exp_f32_e32 v12, v12
	v_exp_f32_e32 v13, v13
	v_exp_f32_e32 v14, v14
	v_exp_f32_e32 v15, v15
	v_exp_f32_e32 v8, v8
	v_exp_f32_e32 v9, v9
	v_exp_f32_e32 v10, v10
	v_exp_f32_e32 v11, v11
	v_fma_f32 v12, v12, v149, v149
	v_fma_f32 v13, v13, v149, v149
	v_fma_f32 v14, v14, v149, v149
	v_fma_f32 v15, v15, v149, v149
	v_fma_f32 v8, v8, v149, v149
	v_fma_f32 v9, v9, v149, v149
	v_fma_f32 v10, v10, v149, v149
	v_fma_f32 v11, v11, v149, v149
	v_rcp_f32_e32 v12, v12
	v_rcp_f32_e32 v13, v13
	v_rcp_f32_e32 v14, v14
	v_rcp_f32_e32 v15, v15
	v_rcp_f32_e32 v8, v8
	v_rcp_f32_e32 v9, v9
	v_rcp_f32_e32 v10, v10
	v_rcp_f32_e32 v11, v11
	s_mov_b32 s8, 0xf2000
	v_pk_mul_f32 v[4:5], v[4:5], v[12:13]
	v_pk_mul_f32 v[6:7], v[6:7], v[14:15]
	v_pk_mul_f32 v[0:1], v[0:1], v[8:9]
	v_pk_mul_f32 v[2:3], v[2:3], v[10:11]
	v_cvt_pk_bf16_f32 v12, v4, v5
	v_cvt_pk_bf16_f32 v13, v6, v7
	v_cvt_pk_bf16_f32 v14, v0, v1
	v_cvt_pk_bf16_f32 v15, v2, v3
	v_lshl_add_u64 v[178:179], v[176:177], 0, s[8:9]
	global_store_dwordx4 v[178:179], v[12:15], off
	s_andn2_b64 vcc, exec, s[6:7]
	s_mov_b64 s[6:7], -1
	s_cbranch_vccnz .LBB0_237
	s_andn2_b64 vcc, exec, s[12:13]
	s_cbranch_vccnz .LBB0_236
	s_barrier
	s_branch .LBB0_236

; __device__ __forceinline__ unsigned cvtpk(float lo, float hi) { f32x2_t v = {lo, hi}; bf16x2_t b = __builtin_convertvector(v, bf16x2_t); return __builtin_bit_cast(unsigned, b); }
;     __device__ __forceinline__ void operator()(const f32x4 (&acc)[2][2][4][2], const Unit& u, int wr, int wc, int fr, int fq) const {
;         const int row0 = u.pm * BM + wr * 64 + fr, col0 = u.pn * 128 + wc * 32 + 8 * fq;
; #pragma unroll
;         for (int ai = 0; ai < 2; ++ai)
; #pragma unroll
;             for (int m = 0; m < 4; ++m) {
;                 const int row = row0 + ai * HALF + m * 16;
;                 const float rs = 1.0f / sqrtf(ssq_sum(ssq + (size_t)row * 16) * (1.0f / DM) + EPS);
;                 float hv[8];
; #pragma unroll
;                 for (int n = 0; n < 2; ++n)
; #pragma unroll
;                     for (int e = 0; e < 4; ++e) {
;                         const float gg = acc[ai][0][m][n][e] * rs, uu = acc[ai][1][m][n][e] * rs;
;                         const float den = 1.0f + __builtin_amdgcn_exp2f(-gg * LOG2E);
;                         hv[n * 4 + e] = gg * uu * __builtin_amdgcn_rcpf(den);
;                     }
;                 u32x4 w; w.x = cvtpk(hv[0], hv[1]); w.y = cvtpk(hv[2], hv[3]); w.z = cvtpk(hv[4], hv[5]); w.w = cvtpk(hv[6], hv[7]);
;                 *(u32x4*)(H + (size_t)row * DFF + col0) = w;
;             }
.LBB0_1054:
	v_lshl_add_u32 v148, s8, 8, v152
	v_ashrrev_i32_e32 v149, 31, v148
	v_lshlrev_b64 v[144:145], 6, v[148:149]
	v_lshl_add_u64 v[144:145], s[16:17], 0, v[144:145]
	global_load_dwordx4 v[160:163], v[144:145], off
	global_load_dwordx4 v[164:167], v[144:145], off offset:16
	global_load_dwordx4 v[168:171], v[144:145], off offset:32
	global_load_dwordx4 v[172:175], v[144:145], off offset:48
	v_mov_b64_e32 v[146:147], s[14:15]
	v_mad_i64_i32 v[176:177], s[8:9], v148, s51, v[146:147]
	v_lshl_or_b32 v150, s2, 7, v154
	v_mov_b32_e32 v151, 0
	v_lshlrev_b64 v[150:151], 1, v[150:151]
	v_lshl_add_u64 v[176:177], v[176:177], 0, v[150:151]
	s_mov_b32 s8, 0x2000
	s_mov_b32 s9, 0
	v_lshl_add_u64 v[146:147], v[144:145], 0, s[8:9]
	s_waitcnt vmcnt(0)
	v_pk_add_f32 v[160:161], v[160:161], v[162:163]
	v_pk_add_f32 v[164:165], v[164:165], v[166:167]
	v_pk_add_f32 v[168:169], v[168:169], v[170:171]
	v_pk_add_f32 v[172:173], v[172:173], v[174:175]
	v_pk_add_f32 v[160:161], v[160:161], v[164:165]
	v_pk_add_f32 v[168:169], v[168:169], v[172:173]
	v_pk_add_f32 v[160:161], v[160:161], v[168:169]
	v_add_f32_e32 v149, v160, v161
	v_fmamk_f32 v149, v149, 0x3a800000, v158
	v_rsq_f32_e32 v150, v149
	global_load_dwordx4 v[160:163], v[144:145], off offset:1024
	global_load_dwordx4 v[164:167], v[144:145], off offset:1040
	global_load_dwordx4 v[168:171], v[144:145], off offset:1056
	global_load_dwordx4 v[172:175], v[144:145], off offset:1072
	v_pk_mul_f32 v[116:117], v[124:125], v[116:117]
	v_pk_mul_f32 v[118:119], v[126:127], v[118:119]
	v_pk_mul_f32 v[112:113], v[120:121], v[112:113]
	v_pk_mul_f32 v[114:115], v[122:123], v[114:115]
	v_mul_f32_e32 v150, 0xbfb8aa3b, v150
	v_mov_b32_e32 v151, v149
	v_pk_mul_f32 v[124:125], v[124:125], v[150:151] op_sel_hi:[1,0]
	v_pk_mul_f32 v[126:127], v[126:127], v[150:151] op_sel_hi:[1,0]
	v_pk_mul_f32 v[120:121], v[120:121], v[150:151] op_sel_hi:[1,0]
	v_pk_mul_f32 v[122:123], v[122:123], v[150:151] op_sel_hi:[1,0]
	v_exp_f32_e32 v124, v124
	v_exp_f32_e32 v125, v125
	v_exp_f32_e32 v126, v126
	v_exp_f32_e32 v127, v127
	v_exp_f32_e32 v120, v120
	v_exp_f32_e32 v121, v121
	v_exp_f32_e32 v122, v122
	v_exp_f32_e32 v123, v123
	v_fma_f32 v124, v124, v149, v149
	v_fma_f32 v125, v125, v149, v149
	v_fma_f32 v126, v126, v149, v149
	v_fma_f32 v127, v127, v149, v149
	v_fma_f32 v120, v120, v149, v149
	v_fma_f32 v121, v121, v149, v149
	v_fma_f32 v122, v122, v149, v149
	v_fma_f32 v123, v123, v149, v149
	v_rcp_f32_e32 v124, v124
	v_rcp_f32_e32 v125, v125
	v_rcp_f32_e32 v126, v126
	v_rcp_f32_e32 v127, v127
	v_rcp_f32_e32 v120, v120
	v_rcp_f32_e32 v121, v121
	v_rcp_f32_e32 v122, v122
	v_rcp_f32_e32 v123, v123
	v_pk_mul_f32 v[116:117], v[116:117], v[124:125]
	v_pk_mul_f32 v[118:119], v[118:119], v[126:127]
	v_pk_mul_f32 v[112:113], v[112:113], v[120:121]
	v_pk_mul_f32 v[114:115], v[114:115], v[122:123]
	v_cvt_pk_bf16_f32 v124, v116, v117
	v_cvt_pk_bf16_f32 v125, v118, v119
	v_cvt_pk_bf16_f32 v126, v112, v113
	v_cvt_pk_bf16_f32 v127, v114, v115
	global_store_dwordx4 v[176:177], v[124:127], off
	s_waitcnt vmcnt(1)
	v_pk_add_f32 v[160:161], v[160:161], v[162:163]
	v_pk_add_f32 v[164:165], v[164:165], v[166:167]
	v_pk_add_f32 v[168:169], v[168:169], v[170:171]
	v_pk_add_f32 v[172:173], v[172:173], v[174:175]
	v_pk_add_f32 v[160:161], v[160:161], v[164:165]
	v_pk_add_f32 v[168:169], v[168:169], v[172:173]
	v_pk_add_f32 v[160:161], v[160:161], v[168:169]
	v_add_f32_e32 v149, v160, v161
	v_fmamk_f32 v149, v149, 0x3a800000, v158
	v_rsq_f32_e32 v150, v149
	global_load_dwordx4 v[160:163], v[144:145], off offset:2048
	global_load_dwordx4 v[164:167], v[144:145], off offset:2064
	global_load_dwordx4 v[168:171], v[144:145], off offset:2080
	global_load_dwordx4 v[172:175], v[144:145], off offset:2096
	v_pk_mul_f32 v[100:101], v[108:109], v[100:101]
	v_pk_mul_f32 v[102:103], v[110:111], v[102:103]
	v_pk_mul_f32 v[96:97], v[104:105], v[96:97]
	v_pk_mul_f32 v[98:99], v[106:107], v[98:99]
	v_mul_f32_e32 v150, 0xbfb8aa3b, v150
	v_mov_b32_e32 v151, v149
	v_pk_mul_f32 v[108:109], v[108:109], v[150:151] op_sel_hi:[1,0]
	v_pk_mul_f32 v[110:111], v[110:111], v[150:151] op_sel_hi:[1,0]
	v_pk_mul_f32 v[104:105], v[104:105], v[150:151] op_sel_hi:[1,0]
	v_pk_mul_f32 v[106:107], v[106:107], v[150:151] op_sel_hi:[1,0]
	v_exp_f32_e32 v108, v108
	v_exp_f32_e32 v109, v109
	v_exp_f32_e32 v110, v110
	v_exp_f32_e32 v111, v111
	v_exp_f32_e32 v104, v104
	v_exp_f32_e32 v105, v105
	v_exp_f32_e32 v106, v106
	v_exp_f32_e32 v107, v107
	v_fma_f32 v108, v108, v149, v149
	v_fma_f32 v109, v109, v149, v149
	v_fma_f32 v110, v110, v149, v149
	v_fma_f32 v111, v111, v149, v149
	v_fma_f32 v104, v104, v149, v149
	v_fma_f32 v105, v105, v149, v149
	v_fma_f32 v106, v106, v149, v149
	v_fma_f32 v107, v107, v149, v149
	v_rcp_f32_e32 v108, v108
	v_rcp_f32_e32 v109, v109
	v_rcp_f32_e32 v110, v110
	v_rcp_f32_e32 v111, v111
	v_rcp_f32_e32 v104, v104
	v_rcp_f32_e32 v105, v105
	v_rcp_f32_e32 v106, v106
	v_rcp_f32_e32 v107, v107
	s_mov_b32 s8, 0x16000
	v_pk_mul_f32 v[100:101], v[100:101], v[108:109]
	v_pk_mul_f32 v[102:103], v[102:103], v[110:111]
	v_pk_mul_f32 v[96:97], v[96:97], v[104:105]
	v_pk_mul_f32 v[98:99], v[98:99], v[106:107]
	v_cvt_pk_bf16_f32 v108, v100, v101
	v_cvt_pk_bf16_f32 v109, v102, v103
	v_cvt_pk_bf16_f32 v110, v96, v97
	v_cvt_pk_bf16_f32 v111, v98, v99
	v_lshl_add_u64 v[178:179], v[176:177], 0, s[8:9]
	global_store_dwordx4 v[178:179], v[108:111], off
	s_waitcnt vmcnt(1)
; __device__ __forceinline__ unsigned cvtpk(float lo, float hi) { f32x2_t v = {lo, hi}; bf16x2_t b = __builtin_convertvector(v, bf16x2_t); return __builtin_bit_cast(unsigned, b); }
;     __device__ __forceinline__ void operator()(const f32x4 (&acc)[2][2][4][2], const Unit& u, int wr, int wc, int fr, int fq) const {
;         const int row0 = u.pm * BM + wr * 64 + fr, col0 = u.pn * 128 + wc * 32 + 8 * fq;
; #pragma unroll
;         for (int ai = 0; ai < 2; ++ai)
; #pragma unroll
;             for (int m = 0; m < 4; ++m) {
;                 const int row = row0 + ai * HALF + m * 16;
;                 const float rs = 1.0f / sqrtf(ssq_sum(ssq + (size_t)row * 16) * (1.0f / DM) + EPS);
;                 float hv[8];
; #pragma unroll
;                 for (int n = 0; n < 2; ++n)
; #pragma unroll
;                     for (int e = 0; e < 4; ++e) {
;                         const float gg = acc[ai][0][m][n][e] * rs, uu = acc[ai][1][m][n][e] * rs;
;                         const float den = 1.0f + __builtin_amdgcn_exp2f(-gg * LOG2E);
;                         hv[n * 4 + e] = gg * uu * __builtin_amdgcn_rcpf(den);
;                     }
;                 u32x4 w; w.x = cvtpk(hv[0], hv[1]); w.y = cvtpk(hv[2], hv[3]); w.z = cvtpk(hv[4], hv[5]); w.w = cvtpk(hv[6], hv[7]);
;                 *(u32x4*)(H + (size_t)row * DFF + col0) = w;
;             }
	v_pk_add_f32 v[160:161], v[160:161], v[162:163]
	v_pk_add_f32 v[164:165], v[164:165], v[166:167]
	v_pk_add_f32 v[168:169], v[168:169], v[170:171]
	v_pk_add_f32 v[172:173], v[172:173], v[174:175]
	v_pk_add_f32 v[160:161], v[160:161], v[164:165]
	v_pk_add_f32 v[168:169], v[168:169], v[172:173]
	v_pk_add_f32 v[160:161], v[160:161], v[168:169]
	v_add_f32_e32 v149, v160, v161
	v_fmamk_f32 v149, v149, 0x3a800000, v158
	v_rsq_f32_e32 v150, v149
	global_load_dwordx4 v[160:163], v[144:145], off offset:3072
	global_load_dwordx4 v[164:167], v[144:145], off offset:3088
	global_load_dwordx4 v[168:171], v[144:145], off offset:3104
	global_load_dwordx4 v[172:175], v[144:145], off offset:3120
	v_pk_mul_f32 v[84:85], v[92:93], v[84:85]
	v_pk_mul_f32 v[86:87], v[94:95], v[86:87]
	v_pk_mul_f32 v[80:81], v[88:89], v[80:81]
	v_pk_mul_f32 v[82:83], v[90:91], v[82:83]
	v_mul_f32_e32 v150, 0xbfb8aa3b, v150
	v_mov_b32_e32 v151, v149
	v_pk_mul_f32 v[92:93], v[92:93], v[150:151] op_sel_hi:[1,0]
	v_pk_mul_f32 v[94:95], v[94:95], v[150:151] op_sel_hi:[1,0]
	v_pk_mul_f32 v[88:89], v[88:89], v[150:151] op_sel_hi:[1,0]
	v_pk_mul_f32 v[90:91], v[90:91], v[150:151] op_sel_hi:[1,0]
	v_exp_f32_e32 v92, v92
	v_exp_f32_e32 v93, v93
	v_exp_f32_e32 v94, v94
	v_exp_f32_e32 v95, v95
	v_exp_f32_e32 v88, v88
	v_exp_f32_e32 v89, v89
	v_exp_f32_e32 v90, v90
	v_exp_f32_e32 v91, v91
	v_fma_f32 v92, v92, v149, v149
	v_fma_f32 v93, v93, v149, v149
	v_fma_f32 v94, v94, v149, v149
	v_fma_f32 v95, v95, v149, v149
	v_fma_f32 v88, v88, v149, v149
	v_fma_f32 v89, v89, v149, v149
	v_fma_f32 v90, v90, v149, v149
	v_fma_f32 v91, v91, v149, v149
	v_rcp_f32_e32 v92, v92
	v_rcp_f32_e32 v93, v93
	v_rcp_f32_e32 v94, v94
	v_rcp_f32_e32 v95, v95
	v_rcp_f32_e32 v88, v88
	v_rcp_f32_e32 v89, v89
	v_rcp_f32_e32 v90, v90
	v_rcp_f32_e32 v91, v91
	s_mov_b32 s8, 0x2c000
	v_pk_mul_f32 v[84:85], v[84:85], v[92:93]
	v_pk_mul_f32 v[86:87], v[86:87], v[94:95]
	v_pk_mul_f32 v[80:81], v[80:81], v[88:89]
	v_pk_mul_f32 v[82:83], v[82:83], v[90:91]
	v_cvt_pk_bf16_f32 v92, v84, v85
	v_cvt_pk_bf16_f32 v93, v86, v87
	v_cvt_pk_bf16_f32 v94, v80, v81
	v_cvt_pk_bf16_f32 v95, v82, v83
	v_lshl_add_u64 v[178:179], v[176:177], 0, s[8:9]
	global_store_dwordx4 v[178:179], v[92:95], off
	s_waitcnt vmcnt(1)
	v_pk_add_f32 v[160:161], v[160:161], v[162:163]
	v_pk_add_f32 v[164:165], v[164:165], v[166:167]
	v_pk_add_f32 v[168:169], v[168:169], v[170:171]
	v_pk_add_f32 v[172:173], v[172:173], v[174:175]
	v_pk_add_f32 v[160:161], v[160:161], v[164:165]
	v_pk_add_f32 v[168:169], v[168:169], v[172:173]
	v_pk_add_f32 v[160:161], v[160:161], v[168:169]
	v_add_f32_e32 v149, v160, v161
	v_fmamk_f32 v149, v149, 0x3a800000, v158
	v_rsq_f32_e32 v150, v149
	global_load_dwordx4 v[160:163], v[146:147], off
	global_load_dwordx4 v[164:167], v[146:147], off offset:16
	global_load_dwordx4 v[168:171], v[146:147], off offset:32
	global_load_dwordx4 v[172:175], v[146:147], off offset:48
	v_pk_mul_f32 v[68:69], v[76:77], v[68:69]
	v_pk_mul_f32 v[70:71], v[78:79], v[70:71]
	v_pk_mul_f32 v[64:65], v[72:73], v[64:65]
	v_pk_mul_f32 v[66:67], v[74:75], v[66:67]
	v_mul_f32_e32 v150, 0xbfb8aa3b, v150
	v_mov_b32_e32 v151, v149
	v_pk_mul_f32 v[76:77], v[76:77], v[150:151] op_sel_hi:[1,0]
	v_pk_mul_f32 v[78:79], v[78:79], v[150:151] op_sel_hi:[1,0]
	v_pk_mul_f32 v[72:73], v[72:73], v[150:151] op_sel_hi:[1,0]
	v_pk_mul_f32 v[74:75], v[74:75], v[150:151] op_sel_hi:[1,0]
	v_exp_f32_e32 v76, v76
	v_exp_f32_e32 v77, v77
	v_exp_f32_e32 v78, v78
	v_exp_f32_e32 v79, v79
	v_exp_f32_e32 v72, v72
	v_exp_f32_e32 v73, v73
	v_exp_f32_e32 v74, v74
	v_exp_f32_e32 v75, v75
	v_fma_f32 v76, v76, v149, v149
	v_fma_f32 v77, v77, v149, v149
	v_fma_f32 v78, v78, v149, v149
	v_fma_f32 v79, v79, v149, v149
	v_fma_f32 v72, v72, v149, v149
	v_fma_f32 v73, v73, v149, v149
	v_fma_f32 v74, v74, v149, v149
	v_fma_f32 v75, v75, v149, v149
	v_rcp_f32_e32 v76, v76
	v_rcp_f32_e32 v77, v77
	v_rcp_f32_e32 v78, v78
	v_rcp_f32_e32 v79, v79
	v_rcp_f32_e32 v72, v72
	v_rcp_f32_e32 v73, v73
	v_rcp_f32_e32 v74, v74
	v_rcp_f32_e32 v75, v75
	s_mov_b32 s8, 0x42000
	v_pk_mul_f32 v[68:69], v[68:69], v[76:77]
	v_pk_mul_f32 v[70:71], v[70:71], v[78:79]
	v_pk_mul_f32 v[64:65], v[64:65], v[72:73]
	v_pk_mul_f32 v[66:67], v[66:67], v[74:75]
	v_cvt_pk_bf16_f32 v76, v68, v69
	v_cvt_pk_bf16_f32 v77, v70, v71
	v_cvt_pk_bf16_f32 v78, v64, v65
	v_cvt_pk_bf16_f32 v79, v66, v67
	v_lshl_add_u64 v[178:179], v[176:177], 0, s[8:9]
	global_store_dwordx4 v[178:179], v[76:79], off
	s_waitcnt vmcnt(1)
	v_pk_add_f32 v[160:161], v[160:161], v[162:163]
	v_pk_add_f32 v[164:165], v[164:165], v[166:167]
	v_pk_add_f32 v[168:169], v[168:169], v[170:171]
	v_pk_add_f32 v[172:173], v[172:173], v[174:175]
	v_pk_add_f32 v[160:161], v[160:161], v[164:165]
	v_pk_add_f32 v[168:169], v[168:169], v[172:173]
	v_pk_add_f32 v[160:161], v[160:161], v[168:169]
	v_add_f32_e32 v149, v160, v161
	v_fmamk_f32 v149, v149, 0x3a800000, v158
	v_rsq_f32_e32 v150, v149
	global_load_dwordx4 v[160:163], v[146:147], off offset:1024
	global_load_dwordx4 v[164:167], v[146:147], off offset:1040
	global_load_dwordx4 v[168:171], v[146:147], off offset:1056
	global_load_dwordx4 v[172:175], v[146:147], off offset:1072
	v_pk_mul_f32 v[52:53], v[60:61], v[52:53]
	v_pk_mul_f32 v[54:55], v[62:63], v[54:55]
	v_pk_mul_f32 v[48:49], v[56:57], v[48:49]
	v_pk_mul_f32 v[50:51], v[58:59], v[50:51]
	v_mul_f32_e32 v150, 0xbfb8aa3b, v150
	v_mov_b32_e32 v151, v149
	v_pk_mul_f32 v[60:61], v[60:61], v[150:151] op_sel_hi:[1,0]
	v_pk_mul_f32 v[62:63], v[62:63], v[150:151] op_sel_hi:[1,0]
	v_pk_mul_f32 v[56:57], v[56:57], v[150:151] op_sel_hi:[1,0]
	v_pk_mul_f32 v[58:59], v[58:59], v[150:151] op_sel_hi:[1,0]
	v_exp_f32_e32 v60, v60
	v_exp_f32_e32 v61, v61
	v_exp_f32_e32 v62, v62
	v_exp_f32_e32 v63, v63
	v_exp_f32_e32 v56, v56
	v_exp_f32_e32 v57, v57
	v_exp_f32_e32 v58, v58
	v_exp_f32_e32 v59, v59
	v_fma_f32 v60, v60, v149, v149
	v_fma_f32 v61, v61, v149, v149
	v_fma_f32 v62, v62, v149, v149
	v_fma_f32 v63, v63, v149, v149
	v_fma_f32 v56, v56, v149, v149
	v_fma_f32 v57, v57, v149, v149
	v_fma_f32 v58, v58, v149, v149
	v_fma_f32 v59, v59, v149, v149
	v_rcp_f32_e32 v60, v60
	v_rcp_f32_e32 v61, v61
	v_rcp_f32_e32 v62, v62
	v_rcp_f32_e32 v63, v63
	v_rcp_f32_e32 v56, v56
	v_rcp_f32_e32 v57, v57
	v_rcp_f32_e32 v58, v58
	v_rcp_f32_e32 v59, v59
	s_mov_b32 s8, 0xb0000
	v_pk_mul_f32 v[52:53], v[52:53], v[60:61]
	v_pk_mul_f32 v[54:55], v[54:55], v[62:63]
	v_pk_mul_f32 v[48:49], v[48:49], v[56:57]
	v_pk_mul_f32 v[50:51], v[50:51], v[58:59]
	v_cvt_pk_bf16_f32 v60, v52, v53
	v_cvt_pk_bf16_f32 v61, v54, v55
	v_cvt_pk_bf16_f32 v62, v48, v49
	v_cvt_pk_bf16_f32 v63, v50, v51
	v_lshl_add_u64 v[178:179], v[176:177], 0, s[8:9]
	global_store_dwordx4 v[178:179], v[60:63], off
	s_waitcnt vmcnt(1)
; __device__ __forceinline__ unsigned cvtpk(float lo, float hi) { f32x2_t v = {lo, hi}; bf16x2_t b = __builtin_convertvector(v, bf16x2_t); return __builtin_bit_cast(unsigned, b); }
;     __device__ __forceinline__ void operator()(const f32x4 (&acc)[2][2][4][2], const Unit& u, int wr, int wc, int fr, int fq) const {
;         const int row0 = u.pm * BM + wr * 64 + fr, col0 = u.pn * 128 + wc * 32 + 8 * fq;
; #pragma unroll
;         for (int ai = 0; ai < 2; ++ai)
; #pragma unroll
;             for (int m = 0; m < 4; ++m) {
;                 const int row = row0 + ai * HALF + m * 16;
;                 const float rs = 1.0f / sqrtf(ssq_sum(ssq + (size_t)row * 16) * (1.0f / DM) + EPS);
;                 float hv[8];
; #pragma unroll
;                 for (int n = 0; n < 2; ++n)
; #pragma unroll
;                     for (int e = 0; e < 4; ++e) {
;                         const float gg = acc[ai][0][m][n][e] * rs, uu = acc[ai][1][m][n][e] * rs;
;                         const float den = 1.0f + __builtin_amdgcn_exp2f(-gg * LOG2E);
;                         hv[n * 4 + e] = gg * uu * __builtin_amdgcn_rcpf(den);
;                     }
;                 u32x4 w; w.x = cvtpk(hv[0], hv[1]); w.y = cvtpk(hv[2], hv[3]); w.z = cvtpk(hv[4], hv[5]); w.w = cvtpk(hv[6], hv[7]);
;                 *(u32x4*)(H + (size_t)row * DFF + col0) = w;
;             }
	v_pk_add_f32 v[160:161], v[160:161], v[162:163]
	v_pk_add_f32 v[164:165], v[164:165], v[166:167]
	v_pk_add_f32 v[168:169], v[168:169], v[170:171]
	v_pk_add_f32 v[172:173], v[172:173], v[174:175]
	v_pk_add_f32 v[160:161], v[160:161], v[164:165]
	v_pk_add_f32 v[168:169], v[168:169], v[172:173]
	v_pk_add_f32 v[160:161], v[160:161], v[168:169]
	v_add_f32_e32 v149, v160, v161
	v_fmamk_f32 v149, v149, 0x3a800000, v158
	v_rsq_f32_e32 v150, v149
	global_load_dwordx4 v[160:163], v[146:147], off offset:2048
	global_load_dwordx4 v[164:167], v[146:147], off offset:2064
	global_load_dwordx4 v[168:171], v[146:147], off offset:2080
	global_load_dwordx4 v[172:175], v[146:147], off offset:2096
	v_pk_mul_f32 v[36:37], v[44:45], v[36:37]
	v_pk_mul_f32 v[38:39], v[46:47], v[38:39]
	v_pk_mul_f32 v[32:33], v[40:41], v[32:33]
	v_pk_mul_f32 v[34:35], v[42:43], v[34:35]
	v_mul_f32_e32 v150, 0xbfb8aa3b, v150
	v_mov_b32_e32 v151, v149
	v_pk_mul_f32 v[44:45], v[44:45], v[150:151] op_sel_hi:[1,0]
	v_pk_mul_f32 v[46:47], v[46:47], v[150:151] op_sel_hi:[1,0]
	v_pk_mul_f32 v[40:41], v[40:41], v[150:151] op_sel_hi:[1,0]
	v_pk_mul_f32 v[42:43], v[42:43], v[150:151] op_sel_hi:[1,0]
	v_exp_f32_e32 v44, v44
	v_exp_f32_e32 v45, v45
	v_exp_f32_e32 v46, v46
	v_exp_f32_e32 v47, v47
	v_exp_f32_e32 v40, v40
	v_exp_f32_e32 v41, v41
	v_exp_f32_e32 v42, v42
	v_exp_f32_e32 v43, v43
	v_fma_f32 v44, v44, v149, v149
	v_fma_f32 v45, v45, v149, v149
	v_fma_f32 v46, v46, v149, v149
	v_fma_f32 v47, v47, v149, v149
	v_fma_f32 v40, v40, v149, v149
	v_fma_f32 v41, v41, v149, v149
	v_fma_f32 v42, v42, v149, v149
	v_fma_f32 v43, v43, v149, v149
	v_rcp_f32_e32 v44, v44
	v_rcp_f32_e32 v45, v45
	v_rcp_f32_e32 v46, v46
	v_rcp_f32_e32 v47, v47
	v_rcp_f32_e32 v40, v40
	v_rcp_f32_e32 v41, v41
	v_rcp_f32_e32 v42, v42
	v_rcp_f32_e32 v43, v43
	s_mov_b32 s8, 0xc6000
	v_pk_mul_f32 v[36:37], v[36:37], v[44:45]
	v_pk_mul_f32 v[38:39], v[38:39], v[46:47]
	v_pk_mul_f32 v[32:33], v[32:33], v[40:41]
	v_pk_mul_f32 v[34:35], v[34:35], v[42:43]
	v_cvt_pk_bf16_f32 v44, v36, v37
	v_cvt_pk_bf16_f32 v45, v38, v39
	v_cvt_pk_bf16_f32 v46, v32, v33
	v_cvt_pk_bf16_f32 v47, v34, v35
	v_lshl_add_u64 v[178:179], v[176:177], 0, s[8:9]
	global_store_dwordx4 v[178:179], v[44:47], off
	s_waitcnt vmcnt(1)
	v_pk_add_f32 v[160:161], v[160:161], v[162:163]
	v_pk_add_f32 v[164:165], v[164:165], v[166:167]
	v_pk_add_f32 v[168:169], v[168:169], v[170:171]
	v_pk_add_f32 v[172:173], v[172:173], v[174:175]
	v_pk_add_f32 v[160:161], v[160:161], v[164:165]
	v_pk_add_f32 v[168:169], v[168:169], v[172:173]
	v_pk_add_f32 v[160:161], v[160:161], v[168:169]
	v_add_f32_e32 v149, v160, v161
	v_fmamk_f32 v149, v149, 0x3a800000, v158
	v_rsq_f32_e32 v150, v149
	global_load_dwordx4 v[160:163], v[146:147], off offset:3072
	global_load_dwordx4 v[164:167], v[146:147], off offset:3088
	global_load_dwordx4 v[168:171], v[146:147], off offset:3104
	global_load_dwordx4 v[172:175], v[146:147], off offset:3120
	v_pk_mul_f32 v[20:21], v[28:29], v[20:21]
	v_pk_mul_f32 v[22:23], v[30:31], v[22:23]
	v_pk_mul_f32 v[16:17], v[24:25], v[16:17]
	v_pk_mul_f32 v[18:19], v[26:27], v[18:19]
	v_mul_f32_e32 v150, 0xbfb8aa3b, v150
	v_mov_b32_e32 v151, v149
	v_pk_mul_f32 v[28:29], v[28:29], v[150:151] op_sel_hi:[1,0]
	v_pk_mul_f32 v[30:31], v[30:31], v[150:151] op_sel_hi:[1,0]
	v_pk_mul_f32 v[24:25], v[24:25], v[150:151] op_sel_hi:[1,0]
	v_pk_mul_f32 v[26:27], v[26:27], v[150:151] op_sel_hi:[1,0]
	v_exp_f32_e32 v28, v28
	v_exp_f32_e32 v29, v29
	v_exp_f32_e32 v30, v30
	v_exp_f32_e32 v31, v31
	v_exp_f32_e32 v24, v24
	v_exp_f32_e32 v25, v25
	v_exp_f32_e32 v26, v26
	v_exp_f32_e32 v27, v27
	v_fma_f32 v28, v28, v149, v149
	v_fma_f32 v29, v29, v149, v149
	v_fma_f32 v30, v30, v149, v149
	v_fma_f32 v31, v31, v149, v149
	v_fma_f32 v24, v24, v149, v149
	v_fma_f32 v25, v25, v149, v149
	v_fma_f32 v26, v26, v149, v149
	v_fma_f32 v27, v27, v149, v149
	v_rcp_f32_e32 v28, v28
	v_rcp_f32_e32 v29, v29
	v_rcp_f32_e32 v30, v30
	v_rcp_f32_e32 v31, v31
	v_rcp_f32_e32 v24, v24
	v_rcp_f32_e32 v25, v25
	v_rcp_f32_e32 v26, v26
	v_rcp_f32_e32 v27, v27
	s_mov_b32 s8, 0xdc000
	v_pk_mul_f32 v[20:21], v[20:21], v[28:29]
	v_pk_mul_f32 v[22:23], v[22:23], v[30:31]
	v_pk_mul_f32 v[16:17], v[16:17], v[24:25]
	v_pk_mul_f32 v[18:19], v[18:19], v[26:27]
	v_cvt_pk_bf16_f32 v28, v20, v21
	v_cvt_pk_bf16_f32 v29, v22, v23
	v_cvt_pk_bf16_f32 v30, v16, v17
	v_cvt_pk_bf16_f32 v31, v18, v19
	v_lshl_add_u64 v[178:179], v[176:177], 0, s[8:9]
	global_store_dwordx4 v[178:179], v[28:31], off
	s_waitcnt vmcnt(1)
	v_pk_add_f32 v[160:161], v[160:161], v[162:163]
	v_pk_add_f32 v[164:165], v[164:165], v[166:167]
	v_pk_add_f32 v[168:169], v[168:169], v[170:171]
	v_pk_add_f32 v[172:173], v[172:173], v[174:175]
	v_pk_add_f32 v[160:161], v[160:161], v[164:165]
	v_pk_add_f32 v[168:169], v[168:169], v[172:173]
	v_pk_add_f32 v[160:161], v[160:161], v[168:169]
	v_add_f32_e32 v149, v160, v161
	v_fmamk_f32 v149, v149, 0x3a800000, v158
	v_rsq_f32_e32 v150, v149
	v_pk_mul_f32 v[4:5], v[12:13], v[4:5]
	v_pk_mul_f32 v[6:7], v[14:15], v[6:7]
	v_pk_mul_f32 v[0:1], v[8:9], v[0:1]
	v_pk_mul_f32 v[2:3], v[10:11], v[2:3]
	v_mul_f32_e32 v150, 0xbfb8aa3b, v150
	v_mov_b32_e32 v151, v149
	v_pk_mul_f32 v[12:13], v[12:13], v[150:151] op_sel_hi:[1,0]
	v_pk_mul_f32 v[14:15], v[14:15], v[150:151] op_sel_hi:[1,0]
	v_pk_mul_f32 v[8:9], v[8:9], v[150:151] op_sel_hi:[1,0]
	v_pk_mul_f32 v[10:11], v[10:11], v[150:151] op_sel_hi:[1,0]
	v_exp_f32_e32 v12, v12
	v_exp_f32_e32 v13, v13
	v_exp_f32_e32 v14, v14
	v_exp_f32_e32 v15, v15
	v_exp_f32_e32 v8, v8
	v_exp_f32_e32 v9, v9
	v_exp_f32_e32 v10, v10
	v_exp_f32_e32 v11, v11
	v_fma_f32 v12, v12, v149, v149
	v_fma_f32 v13, v13, v149, v149
	v_fma_f32 v14, v14, v149, v149
	v_fma_f32 v15, v15, v149, v149
	v_fma_f32 v8, v8, v149, v149
	v_fma_f32 v9, v9, v149, v149
	v_fma_f32 v10, v10, v149, v149
	v_fma_f32 v11, v11, v149, v149
	v_rcp_f32_e32 v12, v12
	v_rcp_f32_e32 v13, v13
	v_rcp_f32_e32 v14, v14
	v_rcp_f32_e32 v15, v15
	v_rcp_f32_e32 v8, v8
	v_rcp_f32_e32 v9, v9
	v_rcp_f32_e32 v10, v10
	v_rcp_f32_e32 v11, v11
	s_mov_b32 s8, 0xf2000
	v_pk_mul_f32 v[4:5], v[4:5], v[12:13]
	v_pk_mul_f32 v[6:7], v[6:7], v[14:15]
	v_pk_mul_f32 v[0:1], v[0:1], v[8:9]
	v_pk_mul_f32 v[2:3], v[2:3], v[10:11]
	v_cvt_pk_bf16_f32 v12, v4, v5
	v_cvt_pk_bf16_f32 v13, v6, v7
	v_cvt_pk_bf16_f32 v14, v0, v1
	v_cvt_pk_bf16_f32 v15, v2, v3
	v_lshl_add_u64 v[178:179], v[176:177], 0, s[8:9]
	global_store_dwordx4 v[178:179], v[12:15], off
	s_andn2_b64 vcc, exec, s[6:7]
	s_mov_b64 s[6:7], -1
	s_cbranch_vccnz .LBB0_1047
	s_andn2_b64 vcc, exec, s[12:13]
	s_cbranch_vccnz .LBB0_1046
	s_barrier
	s_branch .LBB0_1046

; __device__ __forceinline__ float bf2f(unsigned short h) { return __uint_as_float(((unsigned)h) << 16); }
; #define ATT_BAR() do { asm volatile("s_waitcnt lgkmcnt(0)" ::: "memory"); __builtin_amdgcn_s_barrier(); asm volatile("" ::: "memory"); } while (0)
; template <int DQK, int DV, int MODE, int QPRE, bool DIFF> ...
;     ...
;             for (int j = 0; j < 8; ++j) { v[d0][j] = bf2f((unsigned short)qf[d0][j]); s += v[d0][j] * v[d0][j]; }
;         { float a, b; swap32(s, a, b); s = a + b; }
;         const float rs = 1.0f / sqrtf(s * (1.0f / DQK) + EPS);
;     ...
;     ATT_STORE(0, 0); if (DEEP) ATT_STORE(1, (DEEP ? 1 : 0)); ATT_BAR();
.LBB0_1661:
	s_or_b64 exec, exec, s[10:11]
	v_add_f32_e32 v49, v164, v177
	v_fmamk_f32 v49, v49, 0x3c2aaaab, v180
	v_mul_f32_e32 v153, 0x4f800000, v49
	v_cmp_gt_f32_e32 vcc, s48, v49
	s_lshl_b32 s54, s27, 2
	s_lshl_b32 s53, s53, 6
	v_cndmask_b32_e32 v49, v49, v153, vcc
	v_sqrt_f32_e32 v153, v49
	s_add_i32 s55, s54, 4
	s_lshr_b32 s56, s56, 6
	v_add_u32_e32 v186, 0x8800, v184
	v_add_u32_e32 v164, -1, v153
	v_fma_f32 v177, -v164, v153, v49
	v_cmp_ge_f32_e64 s[10:11], 0, v177
	v_add_u32_e32 v177, 1, v153
	v_add_u32_e32 v188, 0, v173
	v_cndmask_b32_e64 v164, v153, v164, s[10:11]
	v_fma_f32 v153, -v177, v153, v49
	v_cmp_lt_f32_e64 s[10:11], 0, v153
	v_add_u32_e32 v189, 0, v174
	s_waitcnt vmcnt(2)
	ds_write2_b64 v186, v[116:117], v[118:119] offset0:128 offset1:130
	v_cndmask_b32_e64 v153, v164, v177, s[10:11]
	v_mul_f32_e32 v164, 0x37800000, v153
	v_cndmask_b32_e32 v153, v153, v164, vcc
	v_cmp_class_f32_e32 vcc, v49, v181
	v_mad_u32_u24 v187, v166, s47, 0
	s_waitcnt lgkmcnt(0)
	s_barrier
; #define LAS __attribute__((address_space(3)))
; __device__ __forceinline__ unsigned cvtpk(float lo, float hi) { f32x2_t v = {lo, hi}; bf16x2_t b = __builtin_convertvector(v, bf16x2_t); return __builtin_bit_cast(unsigned, b); }
; #define ATT_BAR() do { asm volatile("s_waitcnt lgkmcnt(0)" ::: "memory"); __builtin_amdgcn_s_barrier(); asm volatile("" ::: "memory"); } while (0)
; template <int DQK, int DV, int MODE, int QPRE, bool DIFF> ...
;     ...
;         const float rs = 1.0f / sqrtf(s * (1.0f / DQK) + EPS);
; #pragma unroll
;         for (int d0 = 0; d0 < ND0; ++d0) { const f32x4 g0 = *(const f32x4*)(qg + d0 * 16 + hi * 8), g1 = *(const f32x4*)(qg + d0 * 16 + hi * 8 + 4);
; #pragma unroll
;             for (int j = 0; j < 4; ++j) { v[d0][j] *= rs * c * g0[j]; v[d0][4 + j] *= rs * c * g1[j]; } }
;         if (QPRE == 3) {
;             const int pos = q0 + wid * 32 + l32;
; #pragma unroll
;             for (int j = 0; j < 8; ++j) { float cs, sn; rope_cs(pos, 2 * (8 * hi + j), cs, sn); const float x1 = v[ND0 - 2][j], x2 = v[ND0 - 1][j];
;                 v[ND0 - 2][j] = x1 * cs - x2 * sn; v[ND0 - 1][j] = x1 * sn + x2 * cs; }
;         }
; #pragma unroll
;         for (int d0 = 0; d0 < ND0; ++d0) { u32x4 w; w.x = cvtpk(v[d0][0], v[d0][1]); w.y = cvtpk(v[d0][2], v[d0][3]); w.z = cvtpk(v[d0][4], v[d0][5]); w.w = cvtpk(v[d0][6], v[d0][7]); qf[d0] = __builtin_bit_cast(bf16x8, w); }
;     }
;     f32x16 o[NDB];
; #pragma unroll
;     for (int i = 0; i < NDB; ++i)
; #pragma unroll
;         for (int r = 0; r < 16; ++r) o[i][r] = 0.f;
;     float mhat = 0.f, l_run = 0.f, Rp = 1.0f;
;     bool sb_done = false;
;     f32x16 negm;
; #pragma unroll
;     for (int r = 0; r < 16; ++r) negm[r] = 0.f;
;     ...
;         if (DEEP) { if (hf == 1) { if (i0 + 2 < nkt) { ATT_STORE((pp ^ 1) * 2, (DEEP ? 2 * (ph ^ 1) : 0)); ATT_STORE((pp ^ 1) * 2 + 1, (DEEP ? 2 * (ph ^ 1) + 1 : 0)); } ATT_BAR(); pp ^= 1;
;             if (MODE == 1) { sb_stop = (__builtin_amdgcn_readfirstlane((int)*(volatile LAS unsigned*)sbcnt) >= 8); ATT_BAR(); } } }
;         else { if (i + 1 < nkt) ATT_STORE(bi ^ 1, 0); ATT_BAR(); }
	v_cndmask_b32_e32 v49, v153, v49, vcc
	v_div_scale_f32 v153, s[4:5], v49, v49, 1.0
	v_rcp_f32_e32 v164, v153
	s_bfe_u32 s4, s2, 0x30004
	s_mul_i32 s4, s4, 0xc00000
	s_or_b32 s4, s4, s26
	v_fma_f32 v177, -v153, v164, 1.0
	v_fmac_f32_e32 v164, v177, v164
	v_div_scale_f32 v177, vcc, 1.0, v49, 1.0
	v_mul_f32_e32 v178, v177, v164
	v_fma_f32 v179, -v153, v178, v177
	v_fmac_f32_e32 v178, v179, v164
	v_fma_f32 v153, -v153, v178, v177
	v_div_fmas_f32 v153, v153, v164, v178
	v_div_fixup_f32 v49, v153, v49, 1.0
	v_mul_f32_e32 v164, 0x3e16c740, v49
	v_pk_mul_f32 v[4:5], v[164:165], v[4:5] op_sel_hi:[0,1]
	v_pk_mul_f32 v[46:47], v[46:47], v[164:165] op_sel_hi:[1,0]
	v_pk_mul_f32 v[12:13], v[164:165], v[12:13] op_sel_hi:[0,1]
	v_pk_mul_f32 v[4:5], v[4:5], v[64:65]
	v_pk_mul_f32 v[6:7], v[164:165], v[6:7] op_sel_hi:[0,1]
	v_pk_mul_f32 v[46:47], v[46:47], v[50:51]
	v_pk_mul_f32 v[12:13], v[12:13], v[68:69]
	v_pk_mul_f32 v[14:15], v[164:165], v[14:15] op_sel_hi:[0,1]
	v_pk_mul_f32 v[0:1], v[164:165], v[0:1] op_sel_hi:[0,1]
	v_pk_mul_f32 v[6:7], v[6:7], v[70:71]
	v_pk_mul_f32 v[50:51], v[4:5], v[72:73]
	v_pk_mul_f32 v[4:5], v[4:5], v[74:75]
	s_add_u32 s4, s94, s4
	v_pk_mul_f32 v[8:9], v[164:165], v[8:9] op_sel_hi:[0,1]
	v_pk_mul_f32 v[14:15], v[14:15], v[138:139]
	v_pk_mul_f32 v[0:1], v[0:1], v[66:67]
	v_pk_fma_f32 v[50:51], v[12:13], v[74:75], v[50:51] neg_lo:[0,0,1] neg_hi:[0,0,1]
	v_pk_fma_f32 v[4:5], v[12:13], v[72:73], v[4:5]
	v_pk_mul_f32 v[12:13], v[6:7], v[76:77]
	v_pk_mul_f32 v[6:7], v[6:7], v[78:79]
	s_addc_u32 s5, s95, 0
	s_lshl_b32 s2, s2, 9
	v_pk_mul_f32 v[16:17], v[164:165], v[16:17] op_sel_hi:[0,1]
	v_pk_mul_f32 v[18:19], v[164:165], v[18:19] op_sel_hi:[0,1]
	v_pk_mul_f32 v[8:9], v[8:9], v[136:137]
	v_pk_fma_f32 v[12:13], v[14:15], v[78:79], v[12:13] neg_lo:[0,0,1] neg_hi:[0,0,1]
	v_pk_fma_f32 v[6:7], v[14:15], v[76:77], v[6:7]
	v_pk_mul_f32 v[14:15], v[0:1], v[128:129]
	v_pk_mul_f32 v[0:1], v[0:1], v[130:131]
	s_and_b32 s2, s2, 0xe000
	v_pk_mul_f32 v[34:35], v[34:35], v[164:165] op_sel_hi:[1,0]
	v_pk_mul_f32 v[20:21], v[164:165], v[20:21] op_sel_hi:[0,1]
	v_pk_mul_f32 v[16:17], v[16:17], v[142:143]
	v_pk_mul_f32 v[18:19], v[18:19], v[140:141]
	v_pk_mul_f32 v[2:3], v[164:165], v[2:3] op_sel_hi:[0,1]
	v_pk_fma_f32 v[0:1], v[8:9], v[128:129], v[0:1]
	v_mov_b32_e32 v153, v169
	v_mov_b32_e32 v49, v169
	s_add_u32 s2, s58, s2
	v_pk_mul_f32 v[34:35], v[34:35], v[150:151]
	v_pk_mul_f32 v[20:21], v[20:21], v[60:61]
	v_pk_mul_f32 v[10:11], v[164:165], v[10:11] op_sel_hi:[0,1]
	v_pk_mul_f32 v[2:3], v[2:3], v[132:133]
	v_cvt_pk_bf16_f32 v142, v16, v17
	v_cvt_pk_bf16_f32 v143, v18, v19
	v_cvt_pk_bf16_f32 v150, v0, v1
	v_add_u32_e32 v17, s49, v173
	v_add_u32_e32 v18, s49, v174
	v_add3_u32 v19, s50, v172, v175
	v_mov_b32_e32 v0, s50
	v_lshl_add_u64 v[172:173], v[152:153], 1, s[4:5]
	v_lshl_add_u64 v[174:175], v[48:49], 1, s[4:5]
	s_addc_u32 s5, 0, 0
	v_pk_mul_f32 v[44:45], v[44:45], v[164:165] op_sel_hi:[1,0]
	v_pk_mul_f32 v[40:41], v[40:41], v[164:165] op_sel_hi:[1,0]
	v_pk_mul_f32 v[42:43], v[42:43], v[164:165] op_sel_hi:[1,0]
	v_pk_mul_f32 v[36:37], v[36:37], v[164:165] op_sel_hi:[1,0]
	v_pk_mul_f32 v[32:33], v[32:33], v[164:165] op_sel_hi:[1,0]
	v_pk_mul_f32 v[38:39], v[38:39], v[164:165] op_sel_hi:[1,0]
	v_pk_mul_f32 v[28:29], v[28:29], v[164:165] op_sel_hi:[1,0]
	v_pk_mul_f32 v[24:25], v[24:25], v[164:165] op_sel_hi:[1,0]
	v_pk_mul_f32 v[30:31], v[30:31], v[164:165] op_sel_hi:[1,0]
	v_pk_mul_f32 v[26:27], v[26:27], v[164:165] op_sel_hi:[1,0]
	v_pk_mul_f32 v[22:23], v[164:165], v[22:23] op_sel_hi:[0,1]
	v_pk_mul_f32 v[10:11], v[10:11], v[134:135]
	v_pk_fma_f32 v[14:15], v[8:9], v[130:131], v[14:15] neg_lo:[0,0,1] neg_hi:[0,0,1]
	v_pk_mul_f32 v[8:9], v[2:3], v[54:55]
	v_pk_mul_f32 v[2:3], v[2:3], v[56:57]
	v_cvt_pk_bf16_f32 v140, v20, v21
	v_mad_u32_u24 v20, v166, s47, v0
	v_mov_b32_e32 v0, s49
	s_add_u32 s4, s37, s2
	v_pk_mul_f32 v[44:45], v[44:45], v[162:163]
	v_pk_mul_f32 v[40:41], v[40:41], v[160:161]
	v_pk_mul_f32 v[42:43], v[42:43], v[158:159]
	v_pk_mul_f32 v[36:37], v[36:37], v[52:53]
	v_pk_mul_f32 v[32:33], v[32:33], v[156:157]
	v_pk_mul_f32 v[38:39], v[38:39], v[154:155]
	v_pk_mul_f32 v[28:29], v[28:29], v[148:149]
	v_pk_mul_f32 v[24:25], v[24:25], v[146:147]
	v_pk_mul_f32 v[30:31], v[30:31], v[58:59]
	v_pk_mul_f32 v[26:27], v[26:27], v[144:145]
	v_pk_mul_f32 v[22:23], v[22:23], v[62:63]
	v_pk_fma_f32 v[8:9], v[10:11], v[56:57], v[8:9] neg_lo:[0,0,1] neg_hi:[0,0,1]
	v_pk_fma_f32 v[2:3], v[10:11], v[54:55], v[2:3]
	v_cvt_pk_bf16_f32 v146, v14, v15
	v_lshl_add_u32 v16, v166, 6, v187
	v_mad_u32_u24 v21, v166, s46, v0
	v_add_u32_e32 v0, v165, v176
	v_mov_b32_e32 v1, v169
	s_addc_u32 s5, s38, s5
	v_mov_b32_e32 v14, v169
	v_mov_b32_e32 v15, v169
	v_cvt_pk_bf16_f32 v128, v44, v45
	v_cvt_pk_bf16_f32 v129, v46, v47
	v_cvt_pk_bf16_f32 v130, v40, v41
	v_cvt_pk_bf16_f32 v131, v42, v43
	v_cvt_pk_bf16_f32 v132, v36, v37
	v_cvt_pk_bf16_f32 v133, v38, v39
	v_cvt_pk_bf16_f32 v134, v32, v33
	v_cvt_pk_bf16_f32 v135, v34, v35
	v_cvt_pk_bf16_f32 v136, v28, v29
	v_cvt_pk_bf16_f32 v137, v30, v31
	v_cvt_pk_bf16_f32 v138, v24, v25
	v_cvt_pk_bf16_f32 v139, v26, v27
	v_cvt_pk_bf16_f32 v141, v22, v23
	v_cvt_pk_bf16_f32 v145, v12, v13
	v_cvt_pk_bf16_f32 v147, v8, v9
	v_cvt_pk_bf16_f32 v148, v4, v5
	v_cvt_pk_bf16_f32 v149, v6, v7
	v_cvt_pk_bf16_f32 v151, v2, v3
	v_lshl_add_u64 v[176:177], v[0:1], 1, s[4:5]
	v_mov_b32_e32 v0, v169
	v_mov_b32_e32 v2, v169
	v_mov_b32_e32 v3, v169
	v_mov_b32_e32 v4, v169
	v_mov_b32_e32 v5, v169
	v_mov_b32_e32 v6, v169
	v_mov_b32_e32 v7, v169
	v_mov_b32_e32 v8, v169
	v_mov_b32_e32 v9, v169
	v_mov_b32_e32 v10, v169
	v_mov_b32_e32 v11, v169
	v_mov_b32_e32 v12, v169
	v_mov_b32_e32 v13, v169
	v_add_u32_e32 v191, v17, v171
	v_add_u32_e32 v192, v18, v183
	v_add_u32_e32 v193, v19, v167
	v_add_u32_e32 v194, v21, v170
	v_add_u32_e32 v195, v16, v170
	v_add_u32_e32 v197, v20, v170
	v_mov_b64_e32 v[30:31], v[14:15]
	v_mov_b64_e32 v[46:47], v[14:15]
	s_mov_b32 s57, 0
	v_cvt_pk_bf16_f32 v144, v50, v51
	v_mov_b32_e32 v190, 0
	v_mov_b64_e32 v[28:29], v[12:13]
	v_mov_b64_e32 v[26:27], v[10:11]
	v_mov_b64_e32 v[24:25], v[8:9]
	v_mov_b64_e32 v[22:23], v[6:7]
	v_mov_b64_e32 v[20:21], v[4:5]
	v_mov_b64_e32 v[18:19], v[2:3]
	v_mov_b64_e32 v[16:17], v[0:1]
	v_mov_b32_e32 v196, 0
	v_mov_b64_e32 v[44:45], v[12:13]
	v_mov_b64_e32 v[42:43], v[10:11]
	v_mov_b64_e32 v[40:41], v[8:9]
	v_mov_b64_e32 v[38:39], v[6:7]
	v_mov_b64_e32 v[36:37], v[4:5]
	v_mov_b64_e32 v[34:35], v[2:3]
	v_mov_b64_e32 v[32:33], v[0:1]
	s_branch .LBB0_1664
.LBB0_1663:
	s_waitcnt lgkmcnt(0)
	s_barrier
	s_add_i32 s57, s57, 4
	v_lshl_add_u64 v[172:173], v[172:173], 0, s[18:19]
	v_lshl_add_u64 v[174:175], v[174:175], 0, s[18:19]
	s_andn2_b64 vcc, exec, s[10:11]
	v_lshl_add_u64 v[176:177], v[176:177], 0, s[20:21]
	s_cbranch_vccz .LBB0_1636

; #define LAS __attribute__((address_space(3)))
; #define ATT_LOADV(dst, db_) do { const LAS unsigned char* vr_ = vb + (db_) * 32 * VST; _Pragma("unroll") for (int kk = 0; kk < 4; ++kk) dst[kk] = *(const LAS bf16x8*)(vr_ + kk * 32); } while (0)
; template <int DQK, int DV, int MODE, int QPRE, bool DIFF> ...
;     ...
;                 const LAS unsigned char* kb = lds + bi * BUF + l32 * KST + hi * 16;
;             {
;                 const bf16x8 a0 = *(const LAS bf16x8*)(kb), a1 = *(const LAS bf16x8*)(kb + 32 * KST);
;                 if (MODE == 1) { const f32x16 z16 = {0.f, 0.f, 0.f, 0.f, 0.f, 0.f, 0.f, 0.f, 0.f, 0.f, 0.f, 0.f, 0.f, 0.f, 0.f, 0.f};
;                     s0 = __builtin_amdgcn_mfma_f32_32x32x16_bf16(a0, qf[0], z16, 0, 0, 0); s1 = __builtin_amdgcn_mfma_f32_32x32x16_bf16(a1, qf[0], z16, 0, 0, 0); }
;                 else { s0 = __builtin_amdgcn_mfma_f32_32x32x16_bf16(a0, qf[0], negm, 0, 0, 0); s1 = __builtin_amdgcn_mfma_f32_32x32x16_bf16(a1, qf[0], negm, 0, 0, 0); }
;             }
; #pragma unroll
;             for (int d0 = 1; d0 < ND0; ++d0) {
;                 const bf16x8 a0 = *(const LAS bf16x8*)(kb + d0 * 32), a1 = *(const LAS bf16x8*)(kb + 32 * KST + d0 * 32);
;                 s0 = __builtin_amdgcn_mfma_f32_32x32x16_bf16(a0, qf[d0], s0, 0, 0, 0);
;                 s1 = __builtin_amdgcn_mfma_f32_32x32x16_bf16(a1, qf[d0], s1, 0, 0, 0);
;             }
;             }
;             bf16x8 vf[2][4];
;     ...
;             ATT_LOADV(vf[0], 0); if (!DEEP) ATT_LOADV(vf[1], 1);
;             __builtin_amdgcn_sched_barrier(0);
;             if (MODE != 1) {
;                 float mx = fmaxf(s0[0], s1[0]);
; #pragma unroll
;                 for (int r = 1; r < 16; ++r) mx = fmaxf(fmaxf(mx, s0[r]), s1[r]);
;                 { float a, b; swap32(mx, a, b); mx = fmaxf(a, b); }
;                 const bool first = (i == 0);
;                 if (first || __any(mx > 8.0f)) {
;                     const float dl = first ? mx : fmaxf(mx, 0.f);
.LBB0_1674:
	s_cmp_lt_u32 s57, s56
	s_cbranch_scc1 .Lmla_pair0
	ds_read_b128 v[64:67], v195
	ds_read_b128 v[152:155], v195 offset:32
	ds_read_b128 v[156:159], v195 offset:6656
	ds_read_b128 v[160:163], v195 offset:6688
	s_waitcnt lgkmcnt(3)
	v_mfma_f32_32x32x16_bf16 v[48:63], v[64:67], v[128:131], v[32:47]
	s_waitcnt lgkmcnt(1)
	v_mfma_f32_32x32x16_bf16 v[64:79], v[156:159], v[128:131], v[32:47]
	v_mfma_f32_32x32x16_bf16 v[48:63], v[152:155], v[132:135], v[48:63]
	ds_read_b128 v[152:155], v195 offset:64
	ds_read_b128 v[156:159], v195 offset:96
	s_waitcnt lgkmcnt(2)
	v_mfma_f32_32x32x16_bf16 v[64:79], v[160:163], v[132:135], v[64:79]
	s_waitcnt lgkmcnt(1)
	v_mfma_f32_32x32x16_bf16 v[48:63], v[152:155], v[136:139], v[48:63]
	ds_read_b128 v[152:155], v195 offset:6720
	ds_read_b128 v[160:163], v195 offset:6752
	s_waitcnt lgkmcnt(1)
	v_mfma_f32_32x32x16_bf16 v[64:79], v[152:155], v[136:139], v[64:79]
	v_mfma_f32_32x32x16_bf16 v[48:63], v[156:159], v[140:143], v[48:63]
	ds_read_b128 v[152:155], v195 offset:128
	ds_read_b128 v[156:159], v195 offset:160
	s_waitcnt lgkmcnt(2)
	v_mfma_f32_32x32x16_bf16 v[64:79], v[160:163], v[140:143], v[64:79]
	s_waitcnt lgkmcnt(1)
	v_mfma_f32_32x32x16_bf16 v[48:63], v[152:155], v[144:147], v[48:63]
	ds_read_b128 v[152:155], v195 offset:6784
	ds_read_b128 v[200:203], v195 offset:6816
	s_waitcnt lgkmcnt(1)
	v_mfma_f32_32x32x16_bf16 v[64:79], v[152:155], v[144:147], v[64:79]
	v_mfma_f32_32x32x16_bf16 v[48:63], v[156:159], v[148:151], v[48:63]
	ds_read_b128 v[164:167], v198 offset:13312
	ds_read_b128 v[160:163], v198 offset:13344
	ds_read_b128 v[156:159], v198 offset:13376
	ds_read_b128 v[152:155], v198 offset:13408
	s_waitcnt lgkmcnt(4)
	v_mfma_f32_32x32x16_bf16 v[64:79], v[200:203], v[148:151], v[64:79]
	s_nop 11
	v_max_f32_e32 v199, v64, v64
	v_max_f32_e32 v200, v48, v48
	v_max_f32_e32 v199, v200, v199
	v_max3_f32 v199, v199, v49, v65
	v_max3_f32 v199, v199, v50, v66
	v_max3_f32 v199, v199, v51, v67
	v_max3_f32 v199, v199, v52, v68
	v_max3_f32 v199, v199, v53, v69
	v_max3_f32 v199, v199, v54, v70
	v_max3_f32 v199, v199, v55, v71
	v_max3_f32 v199, v199, v56, v72
	v_max3_f32 v199, v199, v57, v73
	v_max3_f32 v199, v199, v58, v74
	v_max3_f32 v199, v199, v59, v75
	v_max3_f32 v199, v199, v60, v76
	v_max3_f32 v199, v199, v61, v77
	v_max3_f32 v199, v199, v62, v78
	v_max3_f32 v199, v199, v63, v79
	v_mov_b32_e32 v200, v199
	s_nop 1
	v_permlane32_swap_b32_e32 v199, v200
	v_max_f32_e32 v200, v200, v200
	v_max_f32_e32 v199, v199, v199
	s_cmp_lg_u32 s57, 0
	s_cselect_b64 s[24:25], -1, 0
	s_cmp_eq_u32 s57, 0
	v_max_f32_e32 v199, v199, v200
	s_cbranch_scc1 .LBB0_1677
	v_cmp_lt_f32_e32 vcc, s51, v199
	s_cbranch_vccz .LBB0_1681
	v_max_f32_e32 v199, v199, v199
	v_max_f32_e32 v199, 0, v199

; #define ATT_BAR() do { asm volatile("s_waitcnt lgkmcnt(0)" ::: "memory"); __builtin_amdgcn_s_barrier(); asm volatile("" ::: "memory"); } while (0)
; template <int DQK, int DV, int MODE, int QPRE, bool DIFF> ...
;     ...
;         if (DEEP) { if (hf == 1) { if (i0 + 2 < nkt) { ATT_STORE((pp ^ 1) * 2, (DEEP ? 2 * (ph ^ 1) : 0)); ATT_STORE((pp ^ 1) * 2 + 1, (DEEP ? 2 * (ph ^ 1) + 1 : 0)); } ATT_BAR(); pp ^= 1;
.LBB0_1689:
	s_cmp_lt_u32 s57, s54
	s_cbranch_scc1 .Lmla_st0
	s_and_saveexec_b64 s[24:25], s[6:7]
	s_cbranch_execz .LBB0_1691
	v_add_u32_e32 v48, v188, v171
	s_waitcnt vmcnt(2)
	ds_write_b128 v48, v[100:103] offset:45056

; template <int DQK, int DV, int MODE, int QPRE, bool DIFF> ...
;     ...
;                 const LAS unsigned char* kb = lds + bi * BUF + l32 * KST + hi * 16;
;             {
;                 const bf16x8 a0 = *(const LAS bf16x8*)(kb), a1 = *(const LAS bf16x8*)(kb + 32 * KST);
;                 if (MODE == 1) { const f32x16 z16 = {0.f, 0.f, 0.f, 0.f, 0.f, 0.f, 0.f, 0.f, 0.f, 0.f, 0.f, 0.f, 0.f, 0.f, 0.f, 0.f};
;                     s0 = __builtin_amdgcn_mfma_f32_32x32x16_bf16(a0, qf[0], z16, 0, 0, 0); s1 = __builtin_amdgcn_mfma_f32_32x32x16_bf16(a1, qf[0], z16, 0, 0, 0); }
;                 else { s0 = __builtin_amdgcn_mfma_f32_32x32x16_bf16(a0, qf[0], negm, 0, 0, 0); s1 = __builtin_amdgcn_mfma_f32_32x32x16_bf16(a1, qf[0], negm, 0, 0, 0); }
;             }
; #pragma unroll
;             for (int d0 = 1; d0 < ND0; ++d0) {
;                 const bf16x8 a0 = *(const LAS bf16x8*)(kb + d0 * 32), a1 = *(const LAS bf16x8*)(kb + 32 * KST + d0 * 32);
;                 s0 = __builtin_amdgcn_mfma_f32_32x32x16_bf16(a0, qf[d0], s0, 0, 0, 0);
;                 s1 = __builtin_amdgcn_mfma_f32_32x32x16_bf16(a1, qf[d0], s1, 0, 0, 0);
;             }
;             }
;             bf16x8 vf[2][4];
;     ...
;             ATT_LOADV(vf[0], 0); if (!DEEP) ATT_LOADV(vf[1], 1);
;             __builtin_amdgcn_sched_barrier(0);
;             if (MODE != 1) {
;                 float mx = fmaxf(s0[0], s1[0]);
; #pragma unroll
;                 for (int r = 1; r < 16; ++r) mx = fmaxf(fmaxf(mx, s0[r]), s1[r]);
;                 { float a, b; swap32(mx, a, b); mx = fmaxf(a, b); }
;                 const bool first = (i == 0);
;                 if (first || __any(mx > 8.0f)) {
;                     const float dl = first ? mx : fmaxf(mx, 0.f);
;                     mhat += dl;
; #pragma unroll
;                     for (int r = 0; r < 16; ++r) { s0[r] -= dl; s1[r] -= dl; negm[r] = -mhat; }
;                     if (DEEP && QKFIRST && hf == 0 && (ATT_TILE(i0 + UNR - 1) <= my_last)) {
; #pragma unroll
;                         for (int r = 0; r < 16; ++r) { sq[UNR - 1][0][r] -= dl; sq[UNR - 1][1][r] -= dl; }
;                     }
;                     if (!first) {
;                         const float alpha = __builtin_amdgcn_exp2f(-dl);
;                         l_run *= alpha;
; #pragma unroll
;                         for (int i2 = 0; i2 < NDB; ++i2)
; #pragma unroll
.LBB0_1708:
	s_add_i32 s2, s57, 2
	s_cmp_lt_u32 s2, s56
	s_cbranch_scc1 .Lmla_pair1
	ds_read_b128 v[64:67], v195 offset:45056
	ds_read_b128 v[152:155], v195 offset:45088
	ds_read_b128 v[156:159], v195 offset:51712
	ds_read_b128 v[160:163], v195 offset:51744
	s_waitcnt lgkmcnt(3)
	v_mfma_f32_32x32x16_bf16 v[48:63], v[64:67], v[128:131], v[32:47]
	s_waitcnt lgkmcnt(1)
	v_mfma_f32_32x32x16_bf16 v[64:79], v[156:159], v[128:131], v[32:47]
	v_mfma_f32_32x32x16_bf16 v[48:63], v[152:155], v[132:135], v[48:63]
	ds_read_b128 v[152:155], v195 offset:45120
	ds_read_b128 v[156:159], v195 offset:45152
	s_waitcnt lgkmcnt(2)
	v_mfma_f32_32x32x16_bf16 v[64:79], v[160:163], v[132:135], v[64:79]
	s_waitcnt lgkmcnt(1)
	v_mfma_f32_32x32x16_bf16 v[48:63], v[152:155], v[136:139], v[48:63]
	ds_read_b128 v[152:155], v195 offset:51776
	ds_read_b128 v[160:163], v195 offset:51808
	s_waitcnt lgkmcnt(1)
	v_mfma_f32_32x32x16_bf16 v[64:79], v[152:155], v[136:139], v[64:79]
	v_mfma_f32_32x32x16_bf16 v[48:63], v[156:159], v[140:143], v[48:63]
	ds_read_b128 v[152:155], v195 offset:45184
	ds_read_b128 v[156:159], v195 offset:45216
	s_waitcnt lgkmcnt(2)
	v_mfma_f32_32x32x16_bf16 v[64:79], v[160:163], v[140:143], v[64:79]
	s_waitcnt lgkmcnt(1)
	v_mfma_f32_32x32x16_bf16 v[48:63], v[152:155], v[144:147], v[48:63]
	ds_read_b128 v[152:155], v195 offset:51840
	ds_read_b128 v[200:203], v195 offset:51872
	s_waitcnt lgkmcnt(1)
	v_mfma_f32_32x32x16_bf16 v[64:79], v[152:155], v[144:147], v[64:79]
	v_mfma_f32_32x32x16_bf16 v[48:63], v[156:159], v[148:151], v[48:63]
	ds_read_b128 v[164:167], v198 offset:58368
	ds_read_b128 v[160:163], v198 offset:58400
	ds_read_b128 v[156:159], v198 offset:58432
	ds_read_b128 v[152:155], v198 offset:58464
	s_waitcnt lgkmcnt(4)
	v_mfma_f32_32x32x16_bf16 v[64:79], v[200:203], v[148:151], v[64:79]
	s_nop 11
	v_max_f32_e32 v178, v64, v64
	v_max_f32_e32 v179, v48, v48
	v_max_f32_e32 v178, v179, v178
	v_max3_f32 v178, v178, v49, v65
	v_max3_f32 v178, v178, v50, v66
	v_max3_f32 v178, v178, v51, v67
	v_max3_f32 v178, v178, v52, v68
	v_max3_f32 v178, v178, v53, v69
	v_max3_f32 v178, v178, v54, v70
	v_max3_f32 v178, v178, v55, v71
	v_max3_f32 v178, v178, v56, v72
	v_max3_f32 v178, v178, v57, v73
	v_max3_f32 v178, v178, v58, v74
	v_max3_f32 v178, v178, v59, v75
	v_max3_f32 v178, v178, v60, v76
	v_max3_f32 v178, v178, v61, v77
	v_max3_f32 v178, v178, v62, v78
	v_max3_f32 v178, v178, v63, v79
	v_mov_b32_e32 v179, v178
	s_nop 1
	v_permlane32_swap_b32_e32 v178, v179
	v_max_f32_e32 v179, v179, v179
	v_max_f32_e32 v178, v178, v178
	v_max_f32_e32 v178, v178, v179
	v_cmp_lt_f32_e32 vcc, s51, v178
	s_cbranch_vccz .LBB0_1710
	v_max_f32_e32 v32, v178, v178
	v_max_f32_e32 v178, 0, v32
	v_exp_f32_e64 v200, -v178
	v_add_f32_e32 v190, v190, v178
	v_xor_b32_e32 v32, 0x80000000, v190
	v_mov_b32_e32 v33, v32
	v_mov_b32_e32 v34, v32
	v_mov_b32_e32 v35, v32
	v_mov_b32_e32 v36, v32
	v_mov_b32_e32 v37, v32
	v_mov_b32_e32 v38, v32
	v_mov_b32_e32 v39, v32
	v_mov_b32_e32 v40, v32
	v_mov_b32_e32 v41, v32
	v_mov_b32_e32 v42, v32
	v_mov_b32_e32 v43, v32
	v_mov_b32_e32 v44, v32
	v_mov_b32_e32 v45, v32
	v_mov_b32_e32 v46, v32
	v_mov_b32_e32 v47, v32
	v_pk_add_f32 v[64:65], v[64:65], v[178:179] op_sel_hi:[1,0] neg_lo:[0,1] neg_hi:[0,1]
	v_pk_add_f32 v[66:67], v[66:67], v[178:179] op_sel_hi:[1,0] neg_lo:[0,1] neg_hi:[0,1]
	v_pk_add_f32 v[68:69], v[68:69], v[178:179] op_sel_hi:[1,0] neg_lo:[0,1] neg_hi:[0,1]
	v_pk_add_f32 v[70:71], v[70:71], v[178:179] op_sel_hi:[1,0] neg_lo:[0,1] neg_hi:[0,1]
	v_pk_add_f32 v[72:73], v[72:73], v[178:179] op_sel_hi:[1,0] neg_lo:[0,1] neg_hi:[0,1]
	v_pk_add_f32 v[74:75], v[74:75], v[178:179] op_sel_hi:[1,0] neg_lo:[0,1] neg_hi:[0,1]
	v_pk_add_f32 v[76:77], v[76:77], v[178:179] op_sel_hi:[1,0] neg_lo:[0,1] neg_hi:[0,1]
	v_pk_add_f32 v[78:79], v[78:79], v[178:179] op_sel_hi:[1,0] neg_lo:[0,1] neg_hi:[0,1]
	v_pk_add_f32 v[48:49], v[48:49], v[178:179] op_sel_hi:[1,0] neg_lo:[0,1] neg_hi:[0,1]
	v_pk_add_f32 v[50:51], v[50:51], v[178:179] op_sel_hi:[1,0] neg_lo:[0,1] neg_hi:[0,1]
	v_pk_add_f32 v[52:53], v[52:53], v[178:179] op_sel_hi:[1,0] neg_lo:[0,1] neg_hi:[0,1]
	v_pk_add_f32 v[54:55], v[54:55], v[178:179] op_sel_hi:[1,0] neg_lo:[0,1] neg_hi:[0,1]
	v_pk_add_f32 v[56:57], v[56:57], v[178:179] op_sel_hi:[1,0] neg_lo:[0,1] neg_hi:[0,1]
	v_pk_add_f32 v[58:59], v[58:59], v[178:179] op_sel_hi:[1,0] neg_lo:[0,1] neg_hi:[0,1]
	v_pk_add_f32 v[60:61], v[60:61], v[178:179] op_sel_hi:[1,0] neg_lo:[0,1] neg_hi:[0,1]
	v_pk_add_f32 v[62:63], v[62:63], v[178:179] op_sel_hi:[1,0] neg_lo:[0,1] neg_hi:[0,1]
	v_pk_mul_f32 v[30:31], v[30:31], v[200:201] op_sel_hi:[1,0]
	v_pk_mul_f32 v[28:29], v[28:29], v[200:201] op_sel_hi:[1,0]
	v_pk_mul_f32 v[26:27], v[26:27], v[200:201] op_sel_hi:[1,0]
	v_pk_mul_f32 v[24:25], v[24:25], v[200:201] op_sel_hi:[1,0]
	v_pk_mul_f32 v[22:23], v[22:23], v[200:201] op_sel_hi:[1,0]
	v_pk_mul_f32 v[20:21], v[20:21], v[200:201] op_sel_hi:[1,0]
	v_pk_mul_f32 v[18:19], v[18:19], v[200:201] op_sel_hi:[1,0]
	v_pk_mul_f32 v[16:17], v[16:17], v[200:201] op_sel_hi:[1,0]
	v_pk_mul_f32 v[14:15], v[14:15], v[200:201] op_sel_hi:[1,0]
	v_pk_mul_f32 v[12:13], v[12:13], v[200:201] op_sel_hi:[1,0]
	v_pk_mul_f32 v[10:11], v[10:11], v[200:201] op_sel_hi:[1,0]
	v_pk_mul_f32 v[8:9], v[8:9], v[200:201] op_sel_hi:[1,0]
	v_pk_mul_f32 v[6:7], v[6:7], v[200:201] op_sel_hi:[1,0]
	v_pk_mul_f32 v[4:5], v[4:5], v[200:201] op_sel_hi:[1,0]
	v_pk_mul_f32 v[2:3], v[2:3], v[200:201] op_sel_hi:[1,0]
	v_pk_mul_f32 v[0:1], v[0:1], v[200:201] op_sel_hi:[1,0]
	v_mul_f32_e32 v196, v196, v200

; #define LAS __attribute__((address_space(3)))
; #define ATT_BAR() do { asm volatile("s_waitcnt lgkmcnt(0)" ::: "memory"); __builtin_amdgcn_s_barrier(); asm volatile("" ::: "memory"); } while (0)
; template <int DQK, int DV, int MODE, int QPRE, bool DIFF> ...
;     ...
;         if (DEEP) { if (hf == 1) { if (i0 + 2 < nkt) { ATT_STORE((pp ^ 1) * 2, (DEEP ? 2 * (ph ^ 1) : 0)); ATT_STORE((pp ^ 1) * 2 + 1, (DEEP ? 2 * (ph ^ 1) + 1 : 0)); } ATT_BAR(); pp ^= 1;
;             if (MODE == 1) { sb_stop = (__builtin_amdgcn_readfirstlane((int)*(volatile LAS unsigned*)sbcnt) >= 8); ATT_BAR(); } } }
;         else { if (i + 1 < nkt) ATT_STORE(bi ^ 1, 0); ATT_BAR(); }
.LBB0_1714:
	v_add_u32_e32 v48, v188, v171
	s_cmp_eq_u64 s[8:9], 0
	s_cbranch_scc1 .Lmla_st1_b
	v_add_u32_e32 v49, v189, v183
	s_waitcnt vmcnt(11)
	ds_write_b128 v48, v[80:83]
	s_waitcnt vmcnt(10)
	ds_write_b128 v49, v[84:87]
	s_waitcnt vmcnt(9)
	ds_write2_b64 v185, v[96:97], v[98:99] offset0:128 offset1:130
	s_waitcnt vmcnt(8)
	ds_write_b128 v48, v[88:91] offset:22528
	s_waitcnt vmcnt(7)
	ds_write_b128 v49, v[92:95] offset:22528
	s_waitcnt vmcnt(6)
	ds_write2_b64 v186, v[116:117], v[118:119] offset0:128 offset1:130
	s_branch .LBB0_1663
.Lmla_st1_b:
	s_waitcnt vmcnt(7)
	ds_write_b128 v48, v[80:83]
	s_waitcnt vmcnt(6)
	ds_write2_b64 v185, v[96:97], v[98:99] offset0:128 offset1:130
	s_waitcnt vmcnt(5)
	ds_write_b128 v48, v[88:91] offset:22528
	s_waitcnt vmcnt(4)
	ds_write2_b64 v186, v[116:117], v[118:119] offset0:128 offset1:130
	s_branch .LBB0_1663

.LBB0_1720:
	v_add_co_u32_e32 v48, vcc, 0x14b50000, v48
	s_nop 1
	v_addc_co_u32_e32 v49, vcc, 0, v49, vcc
	global_load_dwordx4 v[108:111], v[48:49], off
	s_or_b64 exec, exec, s[24:25]
	s_and_saveexec_b64 s[24:25], s[8:9]
	s_cbranch_execnz .LBB0_1706
	s_branch .LBB0_1707
.LBB0_1725:
	ds_write_b128 v49, v[88:91] offset:22528
	s_or_b64 exec, exec, s[4:5]
	s_and_saveexec_b64 s[4:5], vcc
	s_xor_b64 s[4:5], exec, s[4:5]
	s_cbranch_execz .LBB0_1659

; template <int DQK, int DV, int MODE, int QPRE, bool DIFF> ...
;     ...
;                 const LAS unsigned char* kb = lds + bi * BUF + l32 * KST + hi * 16;
;             {
;                 const bf16x8 a0 = *(const LAS bf16x8*)(kb), a1 = *(const LAS bf16x8*)(kb + 32 * KST);
;                 if (MODE == 1) { const f32x16 z16 = {0.f, 0.f, 0.f, 0.f, 0.f, 0.f, 0.f, 0.f, 0.f, 0.f, 0.f, 0.f, 0.f, 0.f, 0.f, 0.f};
;                     s0 = __builtin_amdgcn_mfma_f32_32x32x16_bf16(a0, qf[0], z16, 0, 0, 0); s1 = __builtin_amdgcn_mfma_f32_32x32x16_bf16(a1, qf[0], z16, 0, 0, 0); }
;                 else { s0 = __builtin_amdgcn_mfma_f32_32x32x16_bf16(a0, qf[0], negm, 0, 0, 0); s1 = __builtin_amdgcn_mfma_f32_32x32x16_bf16(a1, qf[0], negm, 0, 0, 0); }
;             }
; #pragma unroll
;             for (int d0 = 1; d0 < ND0; ++d0) {
;                 const bf16x8 a0 = *(const LAS bf16x8*)(kb + d0 * 32), a1 = *(const LAS bf16x8*)(kb + 32 * KST + d0 * 32);
;                 s0 = __builtin_amdgcn_mfma_f32_32x32x16_bf16(a0, qf[d0], s0, 0, 0, 0);
;                 s1 = __builtin_amdgcn_mfma_f32_32x32x16_bf16(a1, qf[d0], s1, 0, 0, 0);
;             }
;             }
;             bf16x8 vf[2][4];
;     ...
;             ATT_LOADV(vf[0], 0); if (!DEEP) ATT_LOADV(vf[1], 1);
;             __builtin_amdgcn_sched_barrier(0);
;             if (MODE != 1) {
;                 float mx = fmaxf(s0[0], s1[0]);
; #pragma unroll
;                 for (int r = 1; r < 16; ++r) mx = fmaxf(fmaxf(mx, s0[r]), s1[r]);
;                 { float a, b; swap32(mx, a, b); mx = fmaxf(a, b); }
;                 const bool first = (i == 0);
;                 if (first || __any(mx > 8.0f)) {
;                     const float dl = first ? mx : fmaxf(mx, 0.f);
;                     mhat += dl;
; #pragma unroll
;                     for (int r = 0; r < 16; ++r) { s0[r] -= dl; s1[r] -= dl; negm[r] = -mhat; }
;                     if (DEEP && QKFIRST && hf == 0 && (ATT_TILE(i0 + UNR - 1) <= my_last)) {
; #pragma unroll
;                         for (int r = 0; r < 16; ++r) { sq[UNR - 1][0][r] -= dl; sq[UNR - 1][1][r] -= dl; }
;                     }
;                     if (!first) {
;                         const float alpha = __builtin_amdgcn_exp2f(-dl);
;                         l_run *= alpha;
; #pragma unroll
;                         for (int i2 = 0; i2 < NDB; ++i2)
; #pragma unroll
.Lmla_st0:
	v_add_u32_e32 v48, v188, v171
	s_cmp_eq_u64 s[8:9], 0
	s_cbranch_scc1 .Lmla_st0_b
	s_waitcnt vmcnt(11)
	ds_write_b128 v48, v[100:103] offset:45056
	v_add_u32_e32 v48, v189, v183
	s_waitcnt vmcnt(10)
	ds_write_b128 v48, v[104:107] offset:45056
	v_add_u32_e32 v48, 0xe000, v184
	s_waitcnt vmcnt(9)
	ds_write2_b64 v48, v[120:121], v[122:123] offset0:128 offset1:130
	s_waitcnt vmcnt(8)
	ds_write_b128 v191, v[108:111]
	s_waitcnt vmcnt(7)
	ds_write_b128 v192, v[112:115]
	s_waitcnt vmcnt(6)
	ds_write2_b64 v193, v[124:125], v[126:127] offset1:2
	s_branch .LBB0_1698
.Lmla_st0_b:
	s_waitcnt vmcnt(7)
	ds_write_b128 v48, v[100:103] offset:45056
	v_add_u32_e32 v48, 0xe000, v184
	s_waitcnt vmcnt(6)
	ds_write2_b64 v48, v[120:121], v[122:123] offset0:128 offset1:130
	s_waitcnt vmcnt(5)
	ds_write_b128 v191, v[108:111]
	s_waitcnt vmcnt(4)
	ds_write2_b64 v193, v[124:125], v[126:127] offset1:2
	s_branch .LBB0_1698
.Lmla_pair0:
	ds_read_b128 v[152:155], v195
	ds_read_b128 v[156:159], v195 offset:6656
	ds_read_b128 v[160:163], v195 offset:32
	ds_read_b128 v[164:167], v195 offset:6688
	ds_read_b128 v[236:239], v195 offset:64
	ds_read_b128 v[240:243], v195 offset:6720
	s_waitcnt lgkmcnt(5)
	v_mfma_f32_32x32x16_bf16 v[48:63], v[152:155], v[128:131], v[32:47]
	ds_read_b128 v[244:247], v195 offset:96
	s_waitcnt lgkmcnt(5)
	v_mfma_f32_32x32x16_bf16 v[64:79], v[156:159], v[128:131], v[32:47]
	ds_read_b128 v[248:251], v195 offset:6752
	s_waitcnt lgkmcnt(5)
	v_mfma_f32_32x32x16_bf16 v[48:63], v[160:163], v[132:135], v[48:63]
	ds_read_b128 v[152:155], v195 offset:128
	s_waitcnt lgkmcnt(5)
	v_mfma_f32_32x32x16_bf16 v[64:79], v[164:167], v[132:135], v[64:79]
	ds_read_b128 v[156:159], v195 offset:6784
	s_waitcnt lgkmcnt(5)
	v_mfma_f32_32x32x16_bf16 v[48:63], v[236:239], v[136:139], v[48:63]
	ds_read_b128 v[160:163], v195 offset:160
	s_waitcnt lgkmcnt(5)
	v_mfma_f32_32x32x16_bf16 v[64:79], v[240:243], v[136:139], v[64:79]
	ds_read_b128 v[164:167], v195 offset:6816
	s_waitcnt lgkmcnt(5)
	v_mfma_f32_32x32x16_bf16 v[48:63], v[244:247], v[140:143], v[48:63]
	ds_read_b128 v[236:239], v195 offset:22528
	s_waitcnt lgkmcnt(5)
	v_mfma_f32_32x32x16_bf16 v[64:79], v[248:251], v[140:143], v[64:79]
	ds_read_b128 v[240:243], v195 offset:29184
	s_waitcnt lgkmcnt(5)
	v_mfma_f32_32x32x16_bf16 v[48:63], v[152:155], v[144:147], v[48:63]
	ds_read_b128 v[244:247], v195 offset:22560
	s_waitcnt lgkmcnt(5)
	v_mfma_f32_32x32x16_bf16 v[64:79], v[156:159], v[144:147], v[64:79]
	ds_read_b128 v[248:251], v195 offset:29216
	s_waitcnt lgkmcnt(5)
	v_mfma_f32_32x32x16_bf16 v[48:63], v[160:163], v[148:151], v[48:63]
	ds_read_b128 v[152:155], v195 offset:22592
	s_waitcnt lgkmcnt(5)
	v_mfma_f32_32x32x16_bf16 v[64:79], v[164:167], v[148:151], v[64:79]
	ds_read_b128 v[156:159], v195 offset:29248
	s_nop 7
	v_max3_f32 v199, v48, v49, v50
	s_nop 1
	v_max3_f32 v252, v64, v65, v66
	v_max3_f32 v199, v199, v51, v52
	v_max3_f32 v252, v252, v67, v68
	v_max3_f32 v199, v199, v53, v54
	v_max3_f32 v252, v252, v69, v70
	v_max3_f32 v199, v199, v55, v56
	v_max3_f32 v252, v252, v71, v72
	v_max3_f32 v199, v199, v57, v58
	v_max3_f32 v252, v252, v73, v74
	v_max3_f32 v199, v199, v59, v60
	v_max3_f32 v252, v252, v75, v76
	v_max3_f32 v199, v199, v61, v62
	v_max3_f32 v252, v252, v77, v78
	v_max3_f32 v199, v199, v63, v79
	v_max_f32_e32 v199, v199, v252
	v_mov_b32_e32 v252, v199
	s_nop 1
	v_permlane32_swap_b32_e32 v199, v252
	v_max_f32_e32 v199, v199, v252
	s_cmp_eq_u32 s57, 0
	s_cbranch_scc1 .Lmla_rare0a
	v_cmp_lt_f32_e32 vcc, s51, v199
	s_cbranch_vccnz .Lmla_rare0a
.Lmla_back0a:
	s_waitcnt lgkmcnt(5)
	v_mfma_f32_32x32x16_bf16 v[204:219], v[236:239], v[128:131], v[32:47]
	ds_read_b128 v[160:163], v195 offset:22624
	v_exp_f32_e32 v48, v48
	v_exp_f32_e32 v49, v49
	v_exp_f32_e32 v50, v50
	v_add_f32_e32 v252, v48, v49
	s_waitcnt lgkmcnt(5)
	v_mfma_f32_32x32x16_bf16 v[220:235], v[240:243], v[128:131], v[32:47]
	ds_read_b128 v[164:167], v195 offset:29280
	v_exp_f32_e32 v51, v51
	v_add_f32_e32 v252, v252, v50
	v_exp_f32_e32 v52, v52
	v_add_f32_e32 v252, v252, v51
	v_exp_f32_e32 v53, v53
	s_waitcnt lgkmcnt(5)
	v_mfma_f32_32x32x16_bf16 v[204:219], v[244:247], v[132:135], v[204:219]
	ds_read_b128 v[236:239], v195 offset:22656
	v_add_f32_e32 v252, v252, v52
	v_exp_f32_e32 v54, v54
	v_add_f32_e32 v252, v252, v53
	v_exp_f32_e32 v55, v55
	s_waitcnt lgkmcnt(5)
	v_mfma_f32_32x32x16_bf16 v[220:235], v[248:251], v[132:135], v[220:235]
	ds_read_b128 v[240:243], v195 offset:29312
	v_add_f32_e32 v252, v252, v54
	v_add_f32_e32 v252, v252, v55
	v_cvt_pk_bf16_f32 v48, v48, v49
	v_cvt_pk_bf16_f32 v49, v50, v51
	v_cvt_pk_bf16_f32 v50, v52, v53
	s_waitcnt lgkmcnt(5)
	v_mfma_f32_32x32x16_bf16 v[204:219], v[152:155], v[136:139], v[204:219]
	ds_read_b128 v[244:247], v195 offset:22688
	v_cvt_pk_bf16_f32 v51, v54, v55
	v_exp_f32_e32 v56, v56
	v_exp_f32_e32 v57, v57
	v_exp_f32_e32 v58, v58
	s_waitcnt lgkmcnt(5)
	v_mfma_f32_32x32x16_bf16 v[220:235], v[156:159], v[136:139], v[220:235]
	ds_read_b128 v[248:251], v195 offset:29344
	v_add_f32_e32 v252, v252, v56
	v_exp_f32_e32 v59, v59
	v_add_f32_e32 v252, v252, v57
	v_exp_f32_e32 v60, v60
	v_add_f32_e32 v252, v252, v58
	s_waitcnt lgkmcnt(5)
	v_mfma_f32_32x32x16_bf16 v[204:219], v[160:163], v[140:143], v[204:219]
	ds_read_b128 v[152:155], v198 offset:13312
	v_exp_f32_e32 v61, v61
	v_add_f32_e32 v252, v252, v59
	v_exp_f32_e32 v62, v62
	v_add_f32_e32 v252, v252, v60
	s_waitcnt lgkmcnt(5)
	v_mfma_f32_32x32x16_bf16 v[220:235], v[164:167], v[140:143], v[220:235]
	ds_read_b128 v[156:159], v198 offset:17920
	v_exp_f32_e32 v63, v63
	v_add_f32_e32 v252, v252, v61
	v_add_f32_e32 v252, v252, v62
	v_add_f32_e32 v252, v252, v63
	v_cvt_pk_bf16_f32 v52, v56, v57
	s_waitcnt lgkmcnt(5)
; template <int DQK, int DV, int MODE, int QPRE, bool DIFF> ...
;     ...
;                 float ls = 0.f;
; #pragma unroll
;                 for (int r = 0; r < 16; ++r) { s0[r] = __builtin_amdgcn_exp2f(s0[r]); s1[r] = __builtin_amdgcn_exp2f(s1[r]); ls = fadd_s(ls, fadd_s(s0[r], s1[r])); }
;                 l_run += ls;
;             } else {
;                 const bool diag = (t == my_last);
;                 const int qrel = q0 + wid * 32 + l32 - t * 64;
;                 float kp[32], gprod[8];
; #pragma unroll
;                 for (int k = 0; k < 8; ++k) {
; #pragma unroll
;                     for (int e = 0; e < 4; ++e) {
;                         const int r = (k & 3) * 4 + e;
;                         const float z2 = __builtin_amdgcn_fmed3f((k < 4) ? s0[r] : s1[r], -126.0f, 126.0f);
;                         const float E = __builtin_amdgcn_exp2f(z2);
;                         const float keep = __builtin_amdgcn_rcpf(fadd_s(E, 1.0f)), beta = fmul_s(E, keep);
;                         kp[k * 4 + e] = keep;
;                         if (k < 4) s0[r] = beta; else s1[r] = beta;
;                     }
;                 }
;                 if (diag) {
;                     asm volatile("" ::: "memory");
; #pragma unroll
;                     for (int k = 0; k < 8; ++k)
; #pragma unroll
;                         for (int e = 0; e < 4; ++e) { const int r = (k & 3) * 4 + e; const int kl = (k >> 2) * 32 + e + 8 * (k & 3) + 4 * hi; const bool valid = kl < qrel;
;                             kp[k * 4 + e] = valid ? kp[k * 4 + e] : 1.0f; if (k < 4) s0[r] = valid ? s0[r] : 0.f; else s1[r] = valid ? s1[r] : 0.f; }
;                 }
; #pragma unroll
;                 for (int k = 0; k < 8; ++k) gprod[k] = fmul_s(fmul_s(kp[k * 4], kp[k * 4 + 1]), fmul_s(kp[k * 4 + 2], kp[k * 4 + 3]));
;                 float base[8]; float suf = 1.0f;
; #pragma unroll
;                 for (int k = 7; k >= 0; --k) { float glo, ghi; swap32(gprod[k], glo, ghi); base[k] = fmul_s(fmul_s(Rp, suf), (hi == 0 ? ghi : 1.0f)); suf = fmul_s(suf, fmul_s(glo, ghi)); }
;                 Rp *= suf;
;                 { const bool nd = __all(Rp == 0.0f); if (nd && !sb_done && lane == 0) __hip_atomic_fetch_add(sbcnt, 1u, __ATOMIC_RELAXED, __HIP_MEMORY_SCOPE_WORKGROUP); sb_done = nd; }
; #pragma unroll
;                 for (int k = 0; k < 8; ++k) {
	v_mfma_f32_32x32x16_bf16 v[204:219], v[236:239], v[144:147], v[204:219]
	ds_read_b128 v[160:163], v198 offset:13344
	v_cvt_pk_bf16_f32 v53, v58, v59
	v_cvt_pk_bf16_f32 v54, v60, v61
	v_cvt_pk_bf16_f32 v55, v62, v63
	v_exp_f32_e32 v64, v64
	s_waitcnt lgkmcnt(5)
	v_mfma_f32_32x32x16_bf16 v[220:235], v[240:243], v[144:147], v[220:235]
	ds_read_b128 v[164:167], v198 offset:17952
	v_exp_f32_e32 v65, v65
	v_exp_f32_e32 v66, v66
	v_add_f32_e32 v253, v64, v65
	v_exp_f32_e32 v67, v67
	s_waitcnt lgkmcnt(5)
	v_mfma_f32_32x32x16_bf16 v[204:219], v[244:247], v[148:151], v[204:219]
	ds_read_b128 v[236:239], v198 offset:13376
	v_add_f32_e32 v253, v253, v66
	v_exp_f32_e32 v68, v68
	v_add_f32_e32 v253, v253, v67
	v_exp_f32_e32 v69, v69
	v_add_f32_e32 v253, v253, v68
	s_waitcnt lgkmcnt(5)
	v_mfma_f32_32x32x16_bf16 v[220:235], v[248:251], v[148:151], v[220:235]
	ds_read_b128 v[240:243], v198 offset:17984
	v_exp_f32_e32 v70, v70
	v_add_f32_e32 v253, v253, v69
	v_exp_f32_e32 v71, v71
	v_add_f32_e32 v253, v253, v70
	s_waitcnt lgkmcnt(5)
	v_mfma_f32_32x32x16_bf16 v[16:31], v[152:155], v[48:51], v[16:31]
	ds_read_b128 v[244:247], v198 offset:13408
	v_add_f32_e32 v253, v253, v71
	v_cvt_pk_bf16_f32 v56, v64, v65
	v_cvt_pk_bf16_f32 v57, v66, v67
	v_cvt_pk_bf16_f32 v58, v68, v69
	v_cvt_pk_bf16_f32 v59, v70, v71
	s_waitcnt lgkmcnt(5)
	v_mfma_f32_32x32x16_bf16 v[0:15], v[156:159], v[48:51], v[0:15]
	ds_read_b128 v[248:251], v198 offset:18016
	v_exp_f32_e32 v72, v72
	v_exp_f32_e32 v73, v73
	v_exp_f32_e32 v74, v74
	v_add_f32_e32 v253, v253, v72
	s_waitcnt lgkmcnt(5)
	v_mfma_f32_32x32x16_bf16 v[16:31], v[160:163], v[52:55], v[16:31]
	ds_read_b128 v[152:155], v198 offset:35840
	v_exp_f32_e32 v75, v75
	v_add_f32_e32 v253, v253, v73
	v_exp_f32_e32 v76, v76
	v_add_f32_e32 v253, v253, v74
	v_exp_f32_e32 v77, v77
	s_waitcnt lgkmcnt(5)
	v_mfma_f32_32x32x16_bf16 v[0:15], v[164:167], v[52:55], v[0:15]
	ds_read_b128 v[156:159], v198 offset:40448
	v_add_f32_e32 v253, v253, v75
	v_exp_f32_e32 v78, v78
	v_add_f32_e32 v253, v253, v76
	v_exp_f32_e32 v79, v79
	s_waitcnt lgkmcnt(5)
	v_mfma_f32_32x32x16_bf16 v[16:31], v[236:239], v[56:59], v[16:31]
	ds_read_b128 v[160:163], v198 offset:35872
	v_add_f32_e32 v253, v253, v77
	v_add_f32_e32 v253, v253, v78
	v_add_f32_e32 v253, v253, v79
	v_cvt_pk_bf16_f32 v60, v72, v73
	v_cvt_pk_bf16_f32 v61, v74, v75
	s_waitcnt lgkmcnt(5)
	v_mfma_f32_32x32x16_bf16 v[0:15], v[240:243], v[56:59], v[0:15]
	ds_read_b128 v[164:167], v198 offset:40480
	v_cvt_pk_bf16_f32 v62, v76, v77
	v_cvt_pk_bf16_f32 v63, v78, v79
	v_add_f32_e32 v252, v252, v253
	v_add_f32_e32 v196, v196, v252
	s_waitcnt lgkmcnt(5)
	v_mfma_f32_32x32x16_bf16 v[16:31], v[244:247], v[60:63], v[16:31]
	ds_read_b128 v[236:239], v198 offset:35904
	s_waitcnt lgkmcnt(5)
	v_mfma_f32_32x32x16_bf16 v[0:15], v[248:251], v[60:63], v[0:15]
	ds_read_b128 v[240:243], v198 offset:40512
	v_max3_f32 v199, v204, v205, v206
	v_max3_f32 v252, v220, v221, v222
	v_max3_f32 v199, v199, v207, v208
	v_max3_f32 v252, v252, v223, v224
	v_max3_f32 v199, v199, v209, v210
	v_max3_f32 v252, v252, v225, v226
	v_max3_f32 v199, v199, v211, v212
	v_max3_f32 v252, v252, v227, v228
	v_max3_f32 v199, v199, v213, v214
	v_max3_f32 v252, v252, v229, v230
	v_max3_f32 v199, v199, v215, v216
	v_max3_f32 v252, v252, v231, v232
	v_max3_f32 v199, v199, v217, v218
	v_max3_f32 v252, v252, v233, v234
	v_max3_f32 v199, v199, v219, v235
	v_max_f32_e32 v199, v199, v252
	v_mov_b32_e32 v252, v199
	s_nop 1
	v_permlane32_swap_b32_e32 v199, v252
	v_max_f32_e32 v199, v199, v252
	v_cmp_lt_f32_e32 vcc, s51, v199
	s_cbranch_vccnz .Lmla_rare0b
.Lmla_back0b:
	v_exp_f32_e32 v204, v204
	v_exp_f32_e32 v205, v205
	v_exp_f32_e32 v206, v206
	v_add_f32_e32 v252, v204, v205
	v_exp_f32_e32 v207, v207
	v_add_f32_e32 v252, v252, v206
	v_exp_f32_e32 v208, v208
	v_add_f32_e32 v252, v252, v207
	v_exp_f32_e32 v209, v209
	v_add_f32_e32 v252, v252, v208
	v_exp_f32_e32 v210, v210
	v_add_f32_e32 v252, v252, v209
	v_exp_f32_e32 v211, v211
	v_add_f32_e32 v252, v252, v210
	v_add_f32_e32 v252, v252, v211
	v_cvt_pk_bf16_f32 v204, v204, v205
	v_cvt_pk_bf16_f32 v205, v206, v207
	v_cvt_pk_bf16_f32 v206, v208, v209
	v_cvt_pk_bf16_f32 v207, v210, v211
	s_waitcnt lgkmcnt(5)
	s_nop 0
	v_mfma_f32_32x32x16_bf16 v[16:31], v[152:155], v[204:207], v[16:31]
	ds_read_b128 v[244:247], v198 offset:35936
	v_exp_f32_e32 v212, v212
	v_exp_f32_e32 v213, v213
	v_exp_f32_e32 v214, v214
	v_add_f32_e32 v252, v252, v212
	v_exp_f32_e32 v215, v215
	v_add_f32_e32 v252, v252, v213
	s_waitcnt lgkmcnt(5)
	v_mfma_f32_32x32x16_bf16 v[0:15], v[156:159], v[204:207], v[0:15]
	ds_read_b128 v[248:251], v198 offset:40544
	v_exp_f32_e32 v216, v216
	v_add_f32_e32 v252, v252, v214
	v_exp_f32_e32 v217, v217
	v_add_f32_e32 v252, v252, v215
	v_exp_f32_e32 v218, v218
	v_add_f32_e32 v252, v252, v216
	v_exp_f32_e32 v219, v219
	v_add_f32_e32 v252, v252, v217
	v_add_f32_e32 v252, v252, v218
	v_add_f32_e32 v252, v252, v219
	v_cvt_pk_bf16_f32 v208, v212, v213
	v_cvt_pk_bf16_f32 v209, v214, v215
	v_cvt_pk_bf16_f32 v210, v216, v217
	v_cvt_pk_bf16_f32 v211, v218, v219
	s_waitcnt lgkmcnt(5)
	s_nop 0
	v_mfma_f32_32x32x16_bf16 v[16:31], v[160:163], v[208:211], v[16:31]
	v_exp_f32_e32 v220, v220
	v_exp_f32_e32 v221, v221
	v_exp_f32_e32 v222, v222
	v_add_f32_e32 v253, v220, v221
	v_exp_f32_e32 v223, v223
	v_add_f32_e32 v253, v253, v222
	s_waitcnt lgkmcnt(4)
	v_mfma_f32_32x32x16_bf16 v[0:15], v[164:167], v[208:211], v[0:15]
	v_exp_f32_e32 v224, v224
	v_add_f32_e32 v253, v253, v223
	v_exp_f32_e32 v225, v225
	v_add_f32_e32 v253, v253, v224
	v_exp_f32_e32 v226, v226
	v_add_f32_e32 v253, v253, v225
	v_exp_f32_e32 v227, v227
	v_add_f32_e32 v253, v253, v226
	v_add_f32_e32 v253, v253, v227
	v_cvt_pk_bf16_f32 v212, v220, v221
	v_cvt_pk_bf16_f32 v213, v222, v223
	v_cvt_pk_bf16_f32 v214, v224, v225
	v_cvt_pk_bf16_f32 v215, v226, v227
	s_waitcnt lgkmcnt(3)
	s_nop 0
	v_mfma_f32_32x32x16_bf16 v[16:31], v[236:239], v[212:215], v[16:31]
	v_exp_f32_e32 v228, v228
	v_exp_f32_e32 v229, v229
	v_exp_f32_e32 v230, v230
	v_add_f32_e32 v253, v253, v228
	v_exp_f32_e32 v231, v231
	v_add_f32_e32 v253, v253, v229
	s_waitcnt lgkmcnt(2)
	v_mfma_f32_32x32x16_bf16 v[0:15], v[240:243], v[212:215], v[0:15]
	v_exp_f32_e32 v232, v232
	v_add_f32_e32 v253, v253, v230
	v_exp_f32_e32 v233, v233
	v_add_f32_e32 v253, v253, v231
	v_exp_f32_e32 v234, v234
	v_add_f32_e32 v253, v253, v232
	v_exp_f32_e32 v235, v235
	v_add_f32_e32 v253, v253, v233
	v_add_f32_e32 v253, v253, v234
	v_add_f32_e32 v253, v253, v235
	v_cvt_pk_bf16_f32 v216, v228, v229
	v_cvt_pk_bf16_f32 v217, v230, v231
	v_cvt_pk_bf16_f32 v218, v232, v233
	v_cvt_pk_bf16_f32 v219, v234, v235
	v_add_f32_e32 v252, v252, v253
	v_add_f32_e32 v196, v196, v252
	s_waitcnt lgkmcnt(1)
	v_mfma_f32_32x32x16_bf16 v[16:31], v[244:247], v[216:219], v[16:31]
	s_waitcnt lgkmcnt(0)
	v_mfma_f32_32x32x16_bf16 v[0:15], v[248:251], v[216:219], v[0:15]
	s_branch .LBB0_1667
; template <int DQK, int DV, int MODE, int QPRE, bool DIFF> ...
;     ...
;                 if (first || __any(mx > 8.0f)) {
;                     const float dl = first ? mx : fmaxf(mx, 0.f);
;                     mhat += dl;
; #pragma unroll
;                     for (int r = 0; r < 16; ++r) { s0[r] -= dl; s1[r] -= dl; negm[r] = -mhat; }
;                     if (DEEP && QKFIRST && hf == 0 && (ATT_TILE(i0 + UNR - 1) <= my_last)) {
; #pragma unroll
;                         for (int r = 0; r < 16; ++r) { sq[UNR - 1][0][r] -= dl; sq[UNR - 1][1][r] -= dl; }
;                     }
;                     if (!first) {
;                         const float alpha = __builtin_amdgcn_exp2f(-dl);
;                         l_run *= alpha;
; #pragma unroll
;                         for (int i2 = 0; i2 < NDB; ++i2)
; #pragma unroll
;                             for (int r = 0; r < 16; ++r) o[i2][r] *= alpha;
;                     }
;                 }
.Lmla_rare0a:
	s_cmp_eq_u32 s57, 0
	s_cbranch_scc1 .Lmla_rare0a_first
	v_max_f32_e32 v200, 0, v199
	v_exp_f32_e64 v202, -v200
	v_add_f32_e32 v190, v190, v200
	s_nop 11
	v_pk_mul_f32 v[30:31], v[30:31], v[202:203] op_sel_hi:[1,0]
	v_pk_mul_f32 v[28:29], v[28:29], v[202:203] op_sel_hi:[1,0]
	v_pk_mul_f32 v[26:27], v[26:27], v[202:203] op_sel_hi:[1,0]
	v_pk_mul_f32 v[24:25], v[24:25], v[202:203] op_sel_hi:[1,0]
	v_pk_mul_f32 v[22:23], v[22:23], v[202:203] op_sel_hi:[1,0]
	v_pk_mul_f32 v[20:21], v[20:21], v[202:203] op_sel_hi:[1,0]
	v_pk_mul_f32 v[18:19], v[18:19], v[202:203] op_sel_hi:[1,0]
	v_pk_mul_f32 v[16:17], v[16:17], v[202:203] op_sel_hi:[1,0]
	v_pk_mul_f32 v[14:15], v[14:15], v[202:203] op_sel_hi:[1,0]
	v_pk_mul_f32 v[12:13], v[12:13], v[202:203] op_sel_hi:[1,0]
	v_pk_mul_f32 v[10:11], v[10:11], v[202:203] op_sel_hi:[1,0]
	v_pk_mul_f32 v[8:9], v[8:9], v[202:203] op_sel_hi:[1,0]
	v_pk_mul_f32 v[6:7], v[6:7], v[202:203] op_sel_hi:[1,0]
	v_pk_mul_f32 v[4:5], v[4:5], v[202:203] op_sel_hi:[1,0]
	v_pk_mul_f32 v[2:3], v[2:3], v[202:203] op_sel_hi:[1,0]
	v_pk_mul_f32 v[0:1], v[0:1], v[202:203] op_sel_hi:[1,0]
	v_mul_f32_e32 v196, v196, v202
.Lmla_rare0a_common:
	v_xor_b32_e32 v32, 0x80000000, v190
	v_mov_b32_e32 v33, v32
	v_mov_b32_e32 v34, v32
	v_mov_b32_e32 v35, v32
	v_mov_b32_e32 v36, v32
	v_mov_b32_e32 v37, v32
	v_mov_b32_e32 v38, v32
	v_mov_b32_e32 v39, v32
	v_mov_b32_e32 v40, v32
	v_mov_b32_e32 v41, v32
	v_mov_b32_e32 v42, v32
	v_mov_b32_e32 v43, v32
	v_mov_b32_e32 v44, v32
	v_mov_b32_e32 v45, v32
	v_mov_b32_e32 v46, v32
	v_mov_b32_e32 v47, v32
	v_pk_add_f32 v[48:49], v[48:49], v[200:201] op_sel_hi:[1,0] neg_lo:[0,1] neg_hi:[0,1]
	v_pk_add_f32 v[50:51], v[50:51], v[200:201] op_sel_hi:[1,0] neg_lo:[0,1] neg_hi:[0,1]
	v_pk_add_f32 v[52:53], v[52:53], v[200:201] op_sel_hi:[1,0] neg_lo:[0,1] neg_hi:[0,1]
	v_pk_add_f32 v[54:55], v[54:55], v[200:201] op_sel_hi:[1,0] neg_lo:[0,1] neg_hi:[0,1]
	v_pk_add_f32 v[56:57], v[56:57], v[200:201] op_sel_hi:[1,0] neg_lo:[0,1] neg_hi:[0,1]
	v_pk_add_f32 v[58:59], v[58:59], v[200:201] op_sel_hi:[1,0] neg_lo:[0,1] neg_hi:[0,1]
	v_pk_add_f32 v[60:61], v[60:61], v[200:201] op_sel_hi:[1,0] neg_lo:[0,1] neg_hi:[0,1]
	v_pk_add_f32 v[62:63], v[62:63], v[200:201] op_sel_hi:[1,0] neg_lo:[0,1] neg_hi:[0,1]
	v_pk_add_f32 v[64:65], v[64:65], v[200:201] op_sel_hi:[1,0] neg_lo:[0,1] neg_hi:[0,1]
	v_pk_add_f32 v[66:67], v[66:67], v[200:201] op_sel_hi:[1,0] neg_lo:[0,1] neg_hi:[0,1]
	v_pk_add_f32 v[68:69], v[68:69], v[200:201] op_sel_hi:[1,0] neg_lo:[0,1] neg_hi:[0,1]
	v_pk_add_f32 v[70:71], v[70:71], v[200:201] op_sel_hi:[1,0] neg_lo:[0,1] neg_hi:[0,1]
	v_pk_add_f32 v[72:73], v[72:73], v[200:201] op_sel_hi:[1,0] neg_lo:[0,1] neg_hi:[0,1]
	v_pk_add_f32 v[74:75], v[74:75], v[200:201] op_sel_hi:[1,0] neg_lo:[0,1] neg_hi:[0,1]
	v_pk_add_f32 v[76:77], v[76:77], v[200:201] op_sel_hi:[1,0] neg_lo:[0,1] neg_hi:[0,1]
	v_pk_add_f32 v[78:79], v[78:79], v[200:201] op_sel_hi:[1,0] neg_lo:[0,1] neg_hi:[0,1]
	s_nop 1
	s_branch .Lmla_back0a
.Lmla_rare0a_first:
	v_mov_b32_e32 v200, v199
	v_add_f32_e32 v190, v190, v200
	s_branch .Lmla_rare0a_common
.Lmla_rare0b:
	v_max_f32_e32 v200, 0, v199
	v_exp_f32_e64 v202, -v200
	v_add_f32_e32 v190, v190, v200
	s_nop 11
	v_pk_mul_f32 v[30:31], v[30:31], v[202:203] op_sel_hi:[1,0]
	v_pk_mul_f32 v[28:29], v[28:29], v[202:203] op_sel_hi:[1,0]
	v_pk_mul_f32 v[26:27], v[26:27], v[202:203] op_sel_hi:[1,0]
	v_pk_mul_f32 v[24:25], v[24:25], v[202:203] op_sel_hi:[1,0]
	v_pk_mul_f32 v[22:23], v[22:23], v[202:203] op_sel_hi:[1,0]
	v_pk_mul_f32 v[20:21], v[20:21], v[202:203] op_sel_hi:[1,0]
	v_pk_mul_f32 v[18:19], v[18:19], v[202:203] op_sel_hi:[1,0]
	v_pk_mul_f32 v[16:17], v[16:17], v[202:203] op_sel_hi:[1,0]
	v_pk_mul_f32 v[14:15], v[14:15], v[202:203] op_sel_hi:[1,0]
	v_pk_mul_f32 v[12:13], v[12:13], v[202:203] op_sel_hi:[1,0]
	v_pk_mul_f32 v[10:11], v[10:11], v[202:203] op_sel_hi:[1,0]
	v_pk_mul_f32 v[8:9], v[8:9], v[202:203] op_sel_hi:[1,0]
	v_pk_mul_f32 v[6:7], v[6:7], v[202:203] op_sel_hi:[1,0]
	v_pk_mul_f32 v[4:5], v[4:5], v[202:203] op_sel_hi:[1,0]
	v_pk_mul_f32 v[2:3], v[2:3], v[202:203] op_sel_hi:[1,0]
	v_pk_mul_f32 v[0:1], v[0:1], v[202:203] op_sel_hi:[1,0]
	v_mul_f32_e32 v196, v196, v202
.Lmla_rare0b_common:
	v_xor_b32_e32 v32, 0x80000000, v190
	v_mov_b32_e32 v33, v32
	v_mov_b32_e32 v34, v32
	v_mov_b32_e32 v35, v32
	v_mov_b32_e32 v36, v32
	v_mov_b32_e32 v37, v32
	v_mov_b32_e32 v38, v32
	v_mov_b32_e32 v39, v32
	v_mov_b32_e32 v40, v32
	v_mov_b32_e32 v41, v32
	v_mov_b32_e32 v42, v32
	v_mov_b32_e32 v43, v32
	v_mov_b32_e32 v44, v32
	v_mov_b32_e32 v45, v32
	v_mov_b32_e32 v46, v32
	v_mov_b32_e32 v47, v32
	v_pk_add_f32 v[204:205], v[204:205], v[200:201] op_sel_hi:[1,0] neg_lo:[0,1] neg_hi:[0,1]
	v_pk_add_f32 v[206:207], v[206:207], v[200:201] op_sel_hi:[1,0] neg_lo:[0,1] neg_hi:[0,1]
	v_pk_add_f32 v[208:209], v[208:209], v[200:201] op_sel_hi:[1,0] neg_lo:[0,1] neg_hi:[0,1]
	v_pk_add_f32 v[210:211], v[210:211], v[200:201] op_sel_hi:[1,0] neg_lo:[0,1] neg_hi:[0,1]
	v_pk_add_f32 v[212:213], v[212:213], v[200:201] op_sel_hi:[1,0] neg_lo:[0,1] neg_hi:[0,1]
	v_pk_add_f32 v[214:215], v[214:215], v[200:201] op_sel_hi:[1,0] neg_lo:[0,1] neg_hi:[0,1]
	v_pk_add_f32 v[216:217], v[216:217], v[200:201] op_sel_hi:[1,0] neg_lo:[0,1] neg_hi:[0,1]
	v_pk_add_f32 v[218:219], v[218:219], v[200:201] op_sel_hi:[1,0] neg_lo:[0,1] neg_hi:[0,1]
	v_pk_add_f32 v[220:221], v[220:221], v[200:201] op_sel_hi:[1,0] neg_lo:[0,1] neg_hi:[0,1]
	v_pk_add_f32 v[222:223], v[222:223], v[200:201] op_sel_hi:[1,0] neg_lo:[0,1] neg_hi:[0,1]
	v_pk_add_f32 v[224:225], v[224:225], v[200:201] op_sel_hi:[1,0] neg_lo:[0,1] neg_hi:[0,1]
	v_pk_add_f32 v[226:227], v[226:227], v[200:201] op_sel_hi:[1,0] neg_lo:[0,1] neg_hi:[0,1]
	v_pk_add_f32 v[228:229], v[228:229], v[200:201] op_sel_hi:[1,0] neg_lo:[0,1] neg_hi:[0,1]
	v_pk_add_f32 v[230:231], v[230:231], v[200:201] op_sel_hi:[1,0] neg_lo:[0,1] neg_hi:[0,1]
	v_pk_add_f32 v[232:233], v[232:233], v[200:201] op_sel_hi:[1,0] neg_lo:[0,1] neg_hi:[0,1]
	v_pk_add_f32 v[234:235], v[234:235], v[200:201] op_sel_hi:[1,0] neg_lo:[0,1] neg_hi:[0,1]
	s_nop 1
	s_branch .Lmla_back0b
; template <int DQK, int DV, int MODE, int QPRE, bool DIFF> ...
;     ...
;                 const LAS unsigned char* kb = lds + bi * BUF + l32 * KST + hi * 16;
;             {
;                 const bf16x8 a0 = *(const LAS bf16x8*)(kb), a1 = *(const LAS bf16x8*)(kb + 32 * KST);
;                 if (MODE == 1) { const f32x16 z16 = {0.f, 0.f, 0.f, 0.f, 0.f, 0.f, 0.f, 0.f, 0.f, 0.f, 0.f, 0.f, 0.f, 0.f, 0.f, 0.f};
;                     s0 = __builtin_amdgcn_mfma_f32_32x32x16_bf16(a0, qf[0], z16, 0, 0, 0); s1 = __builtin_amdgcn_mfma_f32_32x32x16_bf16(a1, qf[0], z16, 0, 0, 0); }
;                 else { s0 = __builtin_amdgcn_mfma_f32_32x32x16_bf16(a0, qf[0], negm, 0, 0, 0); s1 = __builtin_amdgcn_mfma_f32_32x32x16_bf16(a1, qf[0], negm, 0, 0, 0); }
;             }
; #pragma unroll
;             for (int d0 = 1; d0 < ND0; ++d0) {
;                 const bf16x8 a0 = *(const LAS bf16x8*)(kb + d0 * 32), a1 = *(const LAS bf16x8*)(kb + 32 * KST + d0 * 32);
;                 s0 = __builtin_amdgcn_mfma_f32_32x32x16_bf16(a0, qf[d0], s0, 0, 0, 0);
;                 s1 = __builtin_amdgcn_mfma_f32_32x32x16_bf16(a1, qf[d0], s1, 0, 0, 0);
;             }
;             }
;             bf16x8 vf[2][4];
;     ...
;             ATT_LOADV(vf[0], 0); if (!DEEP) ATT_LOADV(vf[1], 1);
;             __builtin_amdgcn_sched_barrier(0);
;             if (MODE != 1) {
;                 float mx = fmaxf(s0[0], s1[0]);
; #pragma unroll
;                 for (int r = 1; r < 16; ++r) mx = fmaxf(fmaxf(mx, s0[r]), s1[r]);
;                 { float a, b; swap32(mx, a, b); mx = fmaxf(a, b); }
;                 const bool first = (i == 0);
;                 if (first || __any(mx > 8.0f)) {
;                     const float dl = first ? mx : fmaxf(mx, 0.f);
;                     mhat += dl;
; #pragma unroll
;                     for (int r = 0; r < 16; ++r) { s0[r] -= dl; s1[r] -= dl; negm[r] = -mhat; }
;                     if (DEEP && QKFIRST && hf == 0 && (ATT_TILE(i0 + UNR - 1) <= my_last)) {
; #pragma unroll
;                         for (int r = 0; r < 16; ++r) { sq[UNR - 1][0][r] -= dl; sq[UNR - 1][1][r] -= dl; }
;                     }
;                     if (!first) {
;                         const float alpha = __builtin_amdgcn_exp2f(-dl);
;                         l_run *= alpha;
; #pragma unroll
;                         for (int i2 = 0; i2 < NDB; ++i2)
; #pragma unroll
.Lmla_pair1:
	ds_read_b128 v[152:155], v195 offset:45056
	ds_read_b128 v[156:159], v195 offset:51712
	ds_read_b128 v[160:163], v195 offset:45088
	ds_read_b128 v[164:167], v195 offset:51744
	ds_read_b128 v[236:239], v195 offset:45120
	ds_read_b128 v[240:243], v195 offset:51776
	s_waitcnt lgkmcnt(5)
	v_mfma_f32_32x32x16_bf16 v[48:63], v[152:155], v[128:131], v[32:47]
	ds_read_b128 v[244:247], v195 offset:45152
	s_waitcnt lgkmcnt(5)
	v_mfma_f32_32x32x16_bf16 v[64:79], v[156:159], v[128:131], v[32:47]
	ds_read_b128 v[248:251], v195 offset:51808
	s_waitcnt lgkmcnt(5)
	v_mfma_f32_32x32x16_bf16 v[48:63], v[160:163], v[132:135], v[48:63]
	ds_read_b128 v[152:155], v195 offset:45184
	s_waitcnt lgkmcnt(5)
	v_mfma_f32_32x32x16_bf16 v[64:79], v[164:167], v[132:135], v[64:79]
	ds_read_b128 v[156:159], v195 offset:51840
	s_waitcnt lgkmcnt(5)
	v_mfma_f32_32x32x16_bf16 v[48:63], v[236:239], v[136:139], v[48:63]
	ds_read_b128 v[160:163], v195 offset:45216
	s_waitcnt lgkmcnt(5)
	v_mfma_f32_32x32x16_bf16 v[64:79], v[240:243], v[136:139], v[64:79]
	ds_read_b128 v[164:167], v195 offset:51872
	s_waitcnt lgkmcnt(5)
	v_mfma_f32_32x32x16_bf16 v[48:63], v[244:247], v[140:143], v[48:63]
	ds_read_b128 v[236:239], v194
	s_waitcnt lgkmcnt(5)
	v_mfma_f32_32x32x16_bf16 v[64:79], v[248:251], v[140:143], v[64:79]
	ds_read_b128 v[240:243], v194 offset:6656
	s_waitcnt lgkmcnt(5)
	v_mfma_f32_32x32x16_bf16 v[48:63], v[152:155], v[144:147], v[48:63]
	ds_read_b128 v[244:247], v194 offset:32
	s_waitcnt lgkmcnt(5)
	v_mfma_f32_32x32x16_bf16 v[64:79], v[156:159], v[144:147], v[64:79]
	ds_read_b128 v[248:251], v194 offset:6688
	s_waitcnt lgkmcnt(5)
	v_mfma_f32_32x32x16_bf16 v[48:63], v[160:163], v[148:151], v[48:63]
	ds_read_b128 v[152:155], v194 offset:64
	s_waitcnt lgkmcnt(5)
	v_mfma_f32_32x32x16_bf16 v[64:79], v[164:167], v[148:151], v[64:79]
	ds_read_b128 v[156:159], v194 offset:6720
	s_nop 7
	v_max3_f32 v199, v48, v49, v50
	s_nop 1
	v_max3_f32 v252, v64, v65, v66
	v_max3_f32 v199, v199, v51, v52
	v_max3_f32 v252, v252, v67, v68
	v_max3_f32 v199, v199, v53, v54
	v_max3_f32 v252, v252, v69, v70
	v_max3_f32 v199, v199, v55, v56
	v_max3_f32 v252, v252, v71, v72
	v_max3_f32 v199, v199, v57, v58
	v_max3_f32 v252, v252, v73, v74
	v_max3_f32 v199, v199, v59, v60
	v_max3_f32 v252, v252, v75, v76
	v_max3_f32 v199, v199, v61, v62
	v_max3_f32 v252, v252, v77, v78
	v_max3_f32 v199, v199, v63, v79
	v_max_f32_e32 v199, v199, v252
	v_mov_b32_e32 v252, v199
	s_nop 1
	v_permlane32_swap_b32_e32 v199, v252
	v_max_f32_e32 v199, v199, v252
	v_cmp_lt_f32_e32 vcc, s51, v199
	s_cbranch_vccnz .Lmla_rare1a
.Lmla_back1a:
	s_waitcnt lgkmcnt(5)
	v_mfma_f32_32x32x16_bf16 v[204:219], v[236:239], v[128:131], v[32:47]
	ds_read_b128 v[160:163], v194 offset:96
	v_exp_f32_e32 v48, v48
	v_exp_f32_e32 v49, v49
	v_exp_f32_e32 v50, v50
	v_add_f32_e32 v252, v48, v49
	s_waitcnt lgkmcnt(5)
	v_mfma_f32_32x32x16_bf16 v[220:235], v[240:243], v[128:131], v[32:47]
	ds_read_b128 v[164:167], v194 offset:6752
	v_exp_f32_e32 v51, v51
	v_add_f32_e32 v252, v252, v50
	v_exp_f32_e32 v52, v52
	v_add_f32_e32 v252, v252, v51
	v_exp_f32_e32 v53, v53
	s_waitcnt lgkmcnt(5)
	v_mfma_f32_32x32x16_bf16 v[204:219], v[244:247], v[132:135], v[204:219]
	ds_read_b128 v[236:239], v194 offset:128
	v_add_f32_e32 v252, v252, v52
	v_exp_f32_e32 v54, v54
	v_add_f32_e32 v252, v252, v53
	v_exp_f32_e32 v55, v55
	s_waitcnt lgkmcnt(5)
	v_mfma_f32_32x32x16_bf16 v[220:235], v[248:251], v[132:135], v[220:235]
	ds_read_b128 v[240:243], v194 offset:6784
	v_add_f32_e32 v252, v252, v54
	v_add_f32_e32 v252, v252, v55
	v_cvt_pk_bf16_f32 v48, v48, v49
	v_cvt_pk_bf16_f32 v49, v50, v51
	v_cvt_pk_bf16_f32 v50, v52, v53
	s_waitcnt lgkmcnt(5)
	v_mfma_f32_32x32x16_bf16 v[204:219], v[152:155], v[136:139], v[204:219]
	ds_read_b128 v[244:247], v194 offset:160
	v_cvt_pk_bf16_f32 v51, v54, v55
	v_exp_f32_e32 v56, v56
	v_exp_f32_e32 v57, v57
	v_exp_f32_e32 v58, v58
	s_waitcnt lgkmcnt(5)
	v_mfma_f32_32x32x16_bf16 v[220:235], v[156:159], v[136:139], v[220:235]
	ds_read_b128 v[248:251], v194 offset:6816
	v_add_f32_e32 v252, v252, v56
	v_exp_f32_e32 v59, v59
	v_add_f32_e32 v252, v252, v57
	v_exp_f32_e32 v60, v60
	v_add_f32_e32 v252, v252, v58
	s_waitcnt lgkmcnt(5)
	v_mfma_f32_32x32x16_bf16 v[204:219], v[160:163], v[140:143], v[204:219]
	ds_read_b128 v[152:155], v198 offset:58368
	v_exp_f32_e32 v61, v61
	v_add_f32_e32 v252, v252, v59
	v_exp_f32_e32 v62, v62
	v_add_f32_e32 v252, v252, v60
	s_waitcnt lgkmcnt(5)
	v_mfma_f32_32x32x16_bf16 v[220:235], v[164:167], v[140:143], v[220:235]
	ds_read_b128 v[156:159], v198 offset:62976
	v_exp_f32_e32 v63, v63
	v_add_f32_e32 v252, v252, v61
	v_add_f32_e32 v252, v252, v62
	v_add_f32_e32 v252, v252, v63
	v_cvt_pk_bf16_f32 v52, v56, v57
	s_waitcnt lgkmcnt(5)
	v_mfma_f32_32x32x16_bf16 v[204:219], v[236:239], v[144:147], v[204:219]
	ds_read_b128 v[160:163], v198 offset:58400
	v_cvt_pk_bf16_f32 v53, v58, v59
	v_cvt_pk_bf16_f32 v54, v60, v61
	v_cvt_pk_bf16_f32 v55, v62, v63
	v_exp_f32_e32 v64, v64
	s_waitcnt lgkmcnt(5)
	v_mfma_f32_32x32x16_bf16 v[220:235], v[240:243], v[144:147], v[220:235]
	ds_read_b128 v[164:167], v198 offset:63008
	v_exp_f32_e32 v65, v65
	v_exp_f32_e32 v66, v66
	v_add_f32_e32 v253, v64, v65
	v_exp_f32_e32 v67, v67
	s_waitcnt lgkmcnt(5)
	v_mfma_f32_32x32x16_bf16 v[204:219], v[244:247], v[148:151], v[204:219]
	ds_read_b128 v[236:239], v198 offset:58432
	v_add_f32_e32 v253, v253, v66
	v_exp_f32_e32 v68, v68
	v_add_f32_e32 v253, v253, v67
	v_exp_f32_e32 v69, v69
	v_add_f32_e32 v253, v253, v68
	s_waitcnt lgkmcnt(5)
; __device__ __forceinline__ float fadd_s(float a, float b) { float r = a + b; asm("" : "+v"(r)); return r; }
; #define ATT_LOADV(dst, db_) do { const LAS unsigned char* vr_ = vb + (db_) * 32 * VST; _Pragma("unroll") for (int kk = 0; kk < 4; ++kk) dst[kk] = *(const LAS bf16x8*)(vr_ + kk * 32); } while (0)
; template <int DQK, int DV, int MODE, int QPRE, bool DIFF> ...
;     ...
;                 float mx = fmaxf(s0[0], s1[0]);
; #pragma unroll
;                 for (int r = 1; r < 16; ++r) mx = fmaxf(fmaxf(mx, s0[r]), s1[r]);
;                 { float a, b; swap32(mx, a, b); mx = fmaxf(a, b); }
;                 const bool first = (i == 0);
;                 if (first || __any(mx > 8.0f)) {
;                     const float dl = first ? mx : fmaxf(mx, 0.f);
;                     mhat += dl;
; #pragma unroll
;                     for (int r = 0; r < 16; ++r) { s0[r] -= dl; s1[r] -= dl; negm[r] = -mhat; }
;                     if (DEEP && QKFIRST && hf == 0 && (ATT_TILE(i0 + UNR - 1) <= my_last)) {
; #pragma unroll
;                         for (int r = 0; r < 16; ++r) { sq[UNR - 1][0][r] -= dl; sq[UNR - 1][1][r] -= dl; }
;                     }
;                     if (!first) {
;                         const float alpha = __builtin_amdgcn_exp2f(-dl);
;                         l_run *= alpha;
; #pragma unroll
;                         for (int i2 = 0; i2 < NDB; ++i2)
; #pragma unroll
;                             for (int r = 0; r < 16; ++r) o[i2][r] *= alpha;
;                     }
;                 }
;                 float ls = 0.f;
; #pragma unroll
;                 for (int r = 0; r < 16; ++r) { s0[r] = __builtin_amdgcn_exp2f(s0[r]); s1[r] = __builtin_amdgcn_exp2f(s1[r]); ls = fadd_s(ls, fadd_s(s0[r], s1[r])); }
;                 l_run += ls;
;     ...
;             for (int dbp = 0; dbp < NDB; dbp += 2) {
; #pragma unroll
;                 for (int kk = 0; kk < 4; ++kk) o[dbp] = __builtin_amdgcn_mfma_f32_32x32x16_bf16(vf[0][kk], pb[kk], o[dbp], 0, 0, 0);
;                 if (DEEP) ATT_LOADV(vf[0], dbp + 1);
; #pragma unroll
;                 for (int kk = 0; kk < 4; ++kk) o[dbp + 1] = __builtin_amdgcn_mfma_f32_32x32x16_bf16(vf[DEEP ? 0 : 1][kk], pb[kk], o[dbp + 1], 0, 0, 0);
;                 if (dbp + 2 < NDB) { ATT_LOADV(vf[0], dbp + 2); ATT_LOADV(vf[1], dbp + 3); }
	v_mfma_f32_32x32x16_bf16 v[220:235], v[248:251], v[148:151], v[220:235]
	ds_read_b128 v[240:243], v198 offset:63040
	v_exp_f32_e32 v70, v70
	v_add_f32_e32 v253, v253, v69
	v_exp_f32_e32 v71, v71
	v_add_f32_e32 v253, v253, v70
	s_waitcnt lgkmcnt(5)
	v_mfma_f32_32x32x16_bf16 v[16:31], v[152:155], v[48:51], v[16:31]
	ds_read_b128 v[244:247], v198 offset:58464
	v_add_f32_e32 v253, v253, v71
	v_cvt_pk_bf16_f32 v56, v64, v65
	v_cvt_pk_bf16_f32 v57, v66, v67
	v_cvt_pk_bf16_f32 v58, v68, v69
	v_cvt_pk_bf16_f32 v59, v70, v71
	s_waitcnt lgkmcnt(5)
	v_mfma_f32_32x32x16_bf16 v[0:15], v[156:159], v[48:51], v[0:15]
	ds_read_b128 v[248:251], v198 offset:63072
	v_exp_f32_e32 v72, v72
	v_exp_f32_e32 v73, v73
	v_exp_f32_e32 v74, v74
	v_add_f32_e32 v253, v253, v72
	s_waitcnt lgkmcnt(5)
	v_mfma_f32_32x32x16_bf16 v[16:31], v[160:163], v[52:55], v[16:31]
	ds_read_b128 v[152:155], v197
	v_exp_f32_e32 v75, v75
	v_add_f32_e32 v253, v253, v73
	v_exp_f32_e32 v76, v76
	v_add_f32_e32 v253, v253, v74
	v_exp_f32_e32 v77, v77
	s_waitcnt lgkmcnt(5)
	v_mfma_f32_32x32x16_bf16 v[0:15], v[164:167], v[52:55], v[0:15]
	ds_read_b128 v[156:159], v197 offset:4608
	v_add_f32_e32 v253, v253, v75
	v_exp_f32_e32 v78, v78
	v_add_f32_e32 v253, v253, v76
	v_exp_f32_e32 v79, v79
	s_waitcnt lgkmcnt(5)
	v_mfma_f32_32x32x16_bf16 v[16:31], v[236:239], v[56:59], v[16:31]
	ds_read_b128 v[160:163], v197 offset:32
	v_add_f32_e32 v253, v253, v77
	v_add_f32_e32 v253, v253, v78
	v_add_f32_e32 v253, v253, v79
	v_cvt_pk_bf16_f32 v60, v72, v73
	v_cvt_pk_bf16_f32 v61, v74, v75
	s_waitcnt lgkmcnt(5)
	v_mfma_f32_32x32x16_bf16 v[0:15], v[240:243], v[56:59], v[0:15]
	ds_read_b128 v[164:167], v197 offset:4640
	v_cvt_pk_bf16_f32 v62, v76, v77
	v_cvt_pk_bf16_f32 v63, v78, v79
	v_add_f32_e32 v252, v252, v253
	v_add_f32_e32 v196, v196, v252
	s_waitcnt lgkmcnt(5)
	v_mfma_f32_32x32x16_bf16 v[16:31], v[244:247], v[60:63], v[16:31]
	ds_read_b128 v[236:239], v197 offset:64
	s_waitcnt lgkmcnt(5)
	v_mfma_f32_32x32x16_bf16 v[0:15], v[248:251], v[60:63], v[0:15]
	ds_read_b128 v[240:243], v197 offset:4672
	v_max3_f32 v199, v204, v205, v206
	v_max3_f32 v252, v220, v221, v222
	v_max3_f32 v199, v199, v207, v208
	v_max3_f32 v252, v252, v223, v224
	v_max3_f32 v199, v199, v209, v210
	v_max3_f32 v252, v252, v225, v226
	v_max3_f32 v199, v199, v211, v212
	v_max3_f32 v252, v252, v227, v228
	v_max3_f32 v199, v199, v213, v214
	v_max3_f32 v252, v252, v229, v230
	v_max3_f32 v199, v199, v215, v216
	v_max3_f32 v252, v252, v231, v232
	v_max3_f32 v199, v199, v217, v218
	v_max3_f32 v252, v252, v233, v234
	v_max3_f32 v199, v199, v219, v235
	v_max_f32_e32 v199, v199, v252
	v_mov_b32_e32 v252, v199
	s_nop 1
	v_permlane32_swap_b32_e32 v199, v252
	v_max_f32_e32 v199, v199, v252
	v_cmp_lt_f32_e32 vcc, s51, v199
	s_cbranch_vccnz .Lmla_rare1b
.Lmla_back1b:
	v_exp_f32_e32 v204, v204
	v_exp_f32_e32 v205, v205
	v_exp_f32_e32 v206, v206
	v_add_f32_e32 v252, v204, v205
	v_exp_f32_e32 v207, v207
	v_add_f32_e32 v252, v252, v206
	v_exp_f32_e32 v208, v208
	v_add_f32_e32 v252, v252, v207
	v_exp_f32_e32 v209, v209
	v_add_f32_e32 v252, v252, v208
	v_exp_f32_e32 v210, v210
	v_add_f32_e32 v252, v252, v209
	v_exp_f32_e32 v211, v211
	v_add_f32_e32 v252, v252, v210
	v_add_f32_e32 v252, v252, v211
	v_cvt_pk_bf16_f32 v204, v204, v205
	v_cvt_pk_bf16_f32 v205, v206, v207
	v_cvt_pk_bf16_f32 v206, v208, v209
	v_cvt_pk_bf16_f32 v207, v210, v211
	s_waitcnt lgkmcnt(5)
	s_nop 0
	v_mfma_f32_32x32x16_bf16 v[16:31], v[152:155], v[204:207], v[16:31]
	ds_read_b128 v[244:247], v197 offset:96
	v_exp_f32_e32 v212, v212
	v_exp_f32_e32 v213, v213
	v_exp_f32_e32 v214, v214
	v_add_f32_e32 v252, v252, v212
	v_exp_f32_e32 v215, v215
	v_add_f32_e32 v252, v252, v213
	s_waitcnt lgkmcnt(5)
	v_mfma_f32_32x32x16_bf16 v[0:15], v[156:159], v[204:207], v[0:15]
	ds_read_b128 v[248:251], v197 offset:4704
	v_exp_f32_e32 v216, v216
	v_add_f32_e32 v252, v252, v214
	v_exp_f32_e32 v217, v217
	v_add_f32_e32 v252, v252, v215
	v_exp_f32_e32 v218, v218
	v_add_f32_e32 v252, v252, v216
	v_exp_f32_e32 v219, v219
	v_add_f32_e32 v252, v252, v217
	v_add_f32_e32 v252, v252, v218
	v_add_f32_e32 v252, v252, v219
	v_cvt_pk_bf16_f32 v208, v212, v213
	v_cvt_pk_bf16_f32 v209, v214, v215
	v_cvt_pk_bf16_f32 v210, v216, v217
	v_cvt_pk_bf16_f32 v211, v218, v219
	s_waitcnt lgkmcnt(5)
	s_nop 0
	v_mfma_f32_32x32x16_bf16 v[16:31], v[160:163], v[208:211], v[16:31]
	v_exp_f32_e32 v220, v220
	v_exp_f32_e32 v221, v221
	v_exp_f32_e32 v222, v222
	v_add_f32_e32 v253, v220, v221
	v_exp_f32_e32 v223, v223
	v_add_f32_e32 v253, v253, v222
	s_waitcnt lgkmcnt(4)
	v_mfma_f32_32x32x16_bf16 v[0:15], v[164:167], v[208:211], v[0:15]
	v_exp_f32_e32 v224, v224
	v_add_f32_e32 v253, v253, v223
	v_exp_f32_e32 v225, v225
	v_add_f32_e32 v253, v253, v224
	v_exp_f32_e32 v226, v226
	v_add_f32_e32 v253, v253, v225
	v_exp_f32_e32 v227, v227
	v_add_f32_e32 v253, v253, v226
	v_add_f32_e32 v253, v253, v227
	v_cvt_pk_bf16_f32 v212, v220, v221
	v_cvt_pk_bf16_f32 v213, v222, v223
	v_cvt_pk_bf16_f32 v214, v224, v225
	v_cvt_pk_bf16_f32 v215, v226, v227
	s_waitcnt lgkmcnt(3)
	s_nop 0
	v_mfma_f32_32x32x16_bf16 v[16:31], v[236:239], v[212:215], v[16:31]
	v_exp_f32_e32 v228, v228
	v_exp_f32_e32 v229, v229
	v_exp_f32_e32 v230, v230
	v_add_f32_e32 v253, v253, v228
	v_exp_f32_e32 v231, v231
	v_add_f32_e32 v253, v253, v229
	s_waitcnt lgkmcnt(2)
	v_mfma_f32_32x32x16_bf16 v[0:15], v[240:243], v[212:215], v[0:15]
	v_exp_f32_e32 v232, v232
	v_add_f32_e32 v253, v253, v230
	v_exp_f32_e32 v233, v233
	v_add_f32_e32 v253, v253, v231
	v_exp_f32_e32 v234, v234
	v_add_f32_e32 v253, v253, v232
	v_exp_f32_e32 v235, v235
	v_add_f32_e32 v253, v253, v233
	v_add_f32_e32 v253, v253, v234
	v_add_f32_e32 v253, v253, v235
	v_cvt_pk_bf16_f32 v216, v228, v229
	v_cvt_pk_bf16_f32 v217, v230, v231
	v_cvt_pk_bf16_f32 v218, v232, v233
	v_cvt_pk_bf16_f32 v219, v234, v235
	v_add_f32_e32 v252, v252, v253
	v_add_f32_e32 v196, v196, v252
	s_waitcnt lgkmcnt(1)
	v_mfma_f32_32x32x16_bf16 v[16:31], v[244:247], v[216:219], v[16:31]
	s_waitcnt lgkmcnt(0)
	v_mfma_f32_32x32x16_bf16 v[0:15], v[248:251], v[216:219], v[0:15]
	s_branch .LBB0_1701
